# ResNorm epilogue: second-half gs/sh vector loads hoisted in front of the first half's stores (in-order vmcnt no longer waits on stores); rope epilogue rewrite; early low-prio MFMAs; deferred retention
# baseline (speedup 1.0000x reference)
.LBB0_395:
	s_ashr_i32 s35, s34, 31
	s_lshl_b64 s[16:17], s[34:35], 13
	s_mul_hi_i32 s15, s34, 0x12000
	s_mul_i32 s14, s34, 0x12000
	s_waitcnt vmcnt(0) lgkmcnt(0)
	s_barrier
	v_lshl_add_u64 v[194:195], v[166:167], 0, s[16:17]
	v_lshl_add_u64 v[196:197], v[168:169], 0, s[14:15]
	global_load_dwordx4 v[138:141], v[194:195], off
	global_load_dwordx4 v[142:145], v[196:197], off
	global_load_dwordx4 v[130:133], v[196:197], off offset:16
	s_waitcnt lgkmcnt(0)
	global_load_dwordx4 v[134:137], v[194:195], off offset:16
	global_load_dwordx4 v[236:239], v[196:197], off offset:512
	global_load_dwordx4 v[240:243], v[194:195], off offset:512
	global_load_dwordx4 v[244:247], v[194:195], off offset:528
	global_load_dwordx4 v[248:251], v[196:197], off offset:528
	ds_read2_b32 v[198:199], v212 offset1:16
	v_lshlrev_b64 v[178:179], 12, v[178:179]
	v_lshlrev_b64 v[200:201], 12, v[180:181]
	v_lshl_add_u64 v[180:181], v[170:171], 0, v[178:179]
	v_lshl_add_u64 v[178:179], v[170:171], 0, v[200:201]
	s_waitcnt lgkmcnt(0)
	v_pk_mul_f32 v[88:89], v[88:89], v[198:199] op_sel_hi:[1,0]
	v_pk_mul_f32 v[86:87], v[86:87], v[198:199] op_sel_hi:[1,0]
	v_pk_mul_f32 v[84:85], v[84:85], v[198:199] op_sel_hi:[1,0]
	v_pk_mul_f32 v[82:83], v[82:83], v[198:199] op_sel_hi:[1,0]
	v_mov_b32_e32 v198, v199
	v_pk_mul_f32 v[112:113], v[112:113], v[198:199] op_sel_hi:[1,0]
	v_pk_mul_f32 v[110:111], v[110:111], v[198:199] op_sel_hi:[1,0]
	v_pk_mul_f32 v[108:109], v[108:109], v[198:199] op_sel_hi:[1,0]
	v_pk_mul_f32 v[106:107], v[106:107], v[198:199] op_sel_hi:[1,0]
	s_andn2_b64 vcc, exec, s[28:29]
	s_mov_b64 s[28:29], -1
	s_waitcnt vmcnt(6)
	v_pk_fma_f32 v[88:89], v[140:141], v[88:89], v[144:145]
	v_pk_fma_f32 v[86:87], v[138:139], v[86:87], v[142:143]
	s_waitcnt vmcnt(4)
	v_pk_fma_f32 v[198:199], v[136:137], v[84:85], v[132:133]
	v_pk_fma_f32 v[84:85], v[134:135], v[82:83], v[130:131]
	v_pk_fma_f32 v[112:113], v[140:141], v[112:113], v[144:145]
	v_pk_fma_f32 v[110:111], v[138:139], v[110:111], v[142:143]
	v_pk_fma_f32 v[108:109], v[136:137], v[108:109], v[132:133]
	v_pk_fma_f32 v[106:107], v[134:135], v[106:107], v[130:131]
	v_cvt_pk_bf16_f32 v82, v86, v87
	v_cvt_pk_bf16_f32 v83, v88, v89
	v_cvt_pk_bf16_f32 v84, v84, v85
	v_cvt_pk_bf16_f32 v85, v198, v199
	v_cvt_pk_bf16_f32 v86, v110, v111
	v_cvt_pk_bf16_f32 v87, v112, v113
	v_cvt_pk_bf16_f32 v88, v106, v107
	v_cvt_pk_bf16_f32 v89, v108, v109
	global_store_dwordx4 v[180:181], v[82:85], off
	global_store_dwordx4 v[178:179], v[86:89], off
	ds_read2_b32 v[86:87], v212 offset0:32 offset1:48
	v_lshlrev_b64 v[82:83], 12, v[182:183]
	v_lshlrev_b64 v[88:89], 12, v[184:185]
	v_lshl_add_u64 v[84:85], v[170:171], 0, v[82:83]
	v_lshl_add_u64 v[82:83], v[170:171], 0, v[88:89]
	s_waitcnt lgkmcnt(0)
	v_pk_mul_f32 v[88:89], v[120:121], v[86:87] op_sel_hi:[1,0]
	v_pk_mul_f32 v[106:107], v[118:119], v[86:87] op_sel_hi:[1,0]
	v_pk_mul_f32 v[108:109], v[116:117], v[86:87] op_sel_hi:[1,0]
	v_pk_mul_f32 v[110:111], v[114:115], v[86:87] op_sel_hi:[1,0]
	v_mov_b32_e32 v86, v87
	v_pk_fma_f32 v[88:89], v[140:141], v[88:89], v[144:145]
	v_pk_fma_f32 v[106:107], v[138:139], v[106:107], v[142:143]
	v_pk_fma_f32 v[108:109], v[136:137], v[108:109], v[132:133]
	v_pk_fma_f32 v[110:111], v[134:135], v[110:111], v[130:131]
	v_pk_mul_f32 v[112:113], v[128:129], v[86:87] op_sel_hi:[1,0]
	v_pk_mul_f32 v[114:115], v[126:127], v[86:87] op_sel_hi:[1,0]
	v_pk_mul_f32 v[116:117], v[124:125], v[86:87] op_sel_hi:[1,0]
	v_pk_mul_f32 v[118:119], v[122:123], v[86:87] op_sel_hi:[1,0]
	v_cvt_pk_bf16_f32 v86, v106, v107
	v_cvt_pk_bf16_f32 v87, v88, v89
	v_cvt_pk_bf16_f32 v88, v110, v111
	v_cvt_pk_bf16_f32 v89, v108, v109
	v_pk_fma_f32 v[106:107], v[140:141], v[112:113], v[144:145]
	v_pk_fma_f32 v[108:109], v[138:139], v[114:115], v[142:143]
	v_pk_fma_f32 v[110:111], v[136:137], v[116:117], v[132:133]
	v_pk_fma_f32 v[112:113], v[134:135], v[118:119], v[130:131]
	global_store_dwordx4 v[84:85], v[86:89], off
	s_nop 1
	v_cvt_pk_bf16_f32 v86, v108, v109
	v_cvt_pk_bf16_f32 v87, v106, v107
	v_cvt_pk_bf16_f32 v88, v112, v113
	v_cvt_pk_bf16_f32 v89, v110, v111
	global_store_dwordx4 v[82:83], v[86:89], off
	ds_read2_b32 v[88:89], v212 offset0:128 offset1:144
	s_waitcnt lgkmcnt(0)
	v_pk_mul_f32 v[104:105], v[104:105], v[88:89] op_sel_hi:[1,0]
	v_pk_mul_f32 v[102:103], v[102:103], v[88:89] op_sel_hi:[1,0]
	v_pk_mul_f32 v[100:101], v[100:101], v[88:89] op_sel_hi:[1,0]
	v_pk_mul_f32 v[98:99], v[98:99], v[88:89] op_sel_hi:[1,0]
	v_mov_b32_e32 v88, v89
	v_lshlrev_b64 v[86:87], 12, v[186:187]
	v_pk_fma_f32 v[104:105], v[140:141], v[104:105], v[144:145]
	v_pk_fma_f32 v[102:103], v[138:139], v[102:103], v[142:143]
	v_pk_fma_f32 v[100:101], v[136:137], v[100:101], v[132:133]
	v_pk_fma_f32 v[98:99], v[134:135], v[98:99], v[130:131]
	v_pk_mul_f32 v[62:63], v[62:63], v[88:89] op_sel_hi:[1,0]
	v_lshl_add_u64 v[86:87], v[170:171], 0, v[86:87]
	v_pk_mul_f32 v[64:65], v[64:65], v[88:89] op_sel_hi:[1,0]
	v_pk_mul_f32 v[106:107], v[60:61], v[88:89] op_sel_hi:[1,0]
	v_pk_mul_f32 v[88:89], v[58:59], v[88:89] op_sel_hi:[1,0]
	v_cvt_pk_bf16_f32 v58, v102, v103
	v_cvt_pk_bf16_f32 v59, v104, v105
	v_cvt_pk_bf16_f32 v60, v98, v99
	v_cvt_pk_bf16_f32 v61, v100, v101
	v_pk_fma_f32 v[62:63], v[138:139], v[62:63], v[142:143]
	v_pk_fma_f32 v[64:65], v[140:141], v[64:65], v[144:145]
	v_pk_fma_f32 v[98:99], v[136:137], v[106:107], v[132:133]
	v_pk_fma_f32 v[88:89], v[134:135], v[88:89], v[130:131]
	global_store_dwordx4 v[86:87], v[58:61], off
	s_nop 1
	v_cvt_pk_bf16_f32 v58, v62, v63
	v_lshlrev_b64 v[62:63], 12, v[188:189]
	v_cvt_pk_bf16_f32 v59, v64, v65
	v_cvt_pk_bf16_f32 v60, v88, v89
	v_cvt_pk_bf16_f32 v61, v98, v99
	v_lshl_add_u64 v[62:63], v[170:171], 0, v[62:63]
	global_store_dwordx4 v[62:63], v[58:61], off
	ds_read2_b32 v[58:59], v212 offset0:160 offset1:176
	s_waitcnt lgkmcnt(0)
	v_pk_mul_f32 v[38:39], v[38:39], v[58:59] op_sel_hi:[1,0]
	v_pk_mul_f32 v[40:41], v[40:41], v[58:59] op_sel_hi:[1,0]
	v_pk_fma_f32 v[38:39], v[138:139], v[38:39], v[142:143]
	v_pk_mul_f32 v[36:37], v[36:37], v[58:59] op_sel_hi:[1,0]
	v_pk_mul_f32 v[34:35], v[34:35], v[58:59] op_sel_hi:[1,0]
	v_pk_fma_f32 v[40:41], v[140:141], v[40:41], v[144:145]
	v_pk_fma_f32 v[60:61], v[136:137], v[36:37], v[132:133]
	v_pk_fma_f32 v[36:37], v[134:135], v[34:35], v[130:131]
	v_cvt_pk_bf16_f32 v34, v38, v39
	v_lshlrev_b64 v[38:39], 12, v[190:191]
	v_cvt_pk_bf16_f32 v35, v40, v41
	v_cvt_pk_bf16_f32 v36, v36, v37
	v_cvt_pk_bf16_f32 v37, v60, v61
	v_lshl_add_u64 v[60:61], v[170:171], 0, v[38:39]
	global_store_dwordx4 v[60:61], v[34:37], off
	s_nop 1
	v_mov_b32_e32 v34, v59
	v_pk_mul_f32 v[14:15], v[14:15], v[34:35] op_sel_hi:[1,0]
	v_pk_mul_f32 v[16:17], v[16:17], v[34:35] op_sel_hi:[1,0]
	v_pk_fma_f32 v[14:15], v[138:139], v[14:15], v[142:143]
	v_pk_mul_f32 v[12:13], v[12:13], v[34:35] op_sel_hi:[1,0]
	v_pk_mul_f32 v[10:11], v[10:11], v[34:35] op_sel_hi:[1,0]
	v_pk_fma_f32 v[16:17], v[140:141], v[16:17], v[144:145]
	v_pk_fma_f32 v[34:35], v[136:137], v[12:13], v[132:133]
	v_pk_fma_f32 v[12:13], v[134:135], v[10:11], v[130:131]
	v_cvt_pk_bf16_f32 v10, v14, v15
	v_lshlrev_b64 v[14:15], 12, v[192:193]
	v_cvt_pk_bf16_f32 v11, v16, v17
	v_cvt_pk_bf16_f32 v12, v12, v13
	v_cvt_pk_bf16_f32 v13, v34, v35
	v_lshl_add_u64 v[58:59], v[170:171], 0, v[14:15]
	global_store_dwordx4 v[58:59], v[10:13], off
	ds_read2_b32 v[64:65], v212 offset1:16
	s_waitcnt lgkmcnt(0)
	v_pk_mul_f32 v[28:29], v[28:29], v[64:65] op_sel_hi:[1,0]
	v_pk_mul_f32 v[26:27], v[26:27], v[64:65] op_sel_hi:[1,0]
	v_pk_mul_f32 v[32:33], v[32:33], v[64:65] op_sel_hi:[1,0]
	v_pk_mul_f32 v[30:31], v[30:31], v[64:65] op_sel_hi:[1,0]
	v_mov_b32_e32 v64, v65
	v_pk_mul_f32 v[44:45], v[44:45], v[64:65] op_sel_hi:[1,0]
	v_pk_mul_f32 v[42:43], v[42:43], v[64:65] op_sel_hi:[1,0]
	v_pk_mul_f32 v[52:53], v[52:53], v[64:65] op_sel_hi:[1,0]
	v_pk_mul_f32 v[50:51], v[50:51], v[64:65] op_sel_hi:[1,0]
	s_waitcnt vmcnt(8)
	v_pk_fma_f32 v[28:29], v[242:243], v[28:29], v[238:239]
	v_pk_fma_f32 v[26:27], v[240:241], v[26:27], v[236:237]
	s_waitcnt vmcnt(8)
	v_pk_fma_f32 v[32:33], v[246:247], v[32:33], v[250:251]
	v_pk_fma_f32 v[30:31], v[244:245], v[30:31], v[248:249]
	v_pk_fma_f32 v[44:45], v[242:243], v[44:45], v[238:239]
	v_pk_fma_f32 v[42:43], v[240:241], v[42:43], v[236:237]
	v_pk_fma_f32 v[52:53], v[246:247], v[52:53], v[250:251]
	v_pk_fma_f32 v[50:51], v[244:245], v[50:51], v[248:249]
	v_cvt_pk_bf16_f32 v26, v26, v27
	v_cvt_pk_bf16_f32 v27, v28, v29
	v_cvt_pk_bf16_f32 v28, v30, v31
	v_cvt_pk_bf16_f32 v29, v32, v33
	v_cvt_pk_bf16_f32 v30, v42, v43
	v_cvt_pk_bf16_f32 v31, v44, v45
	v_cvt_pk_bf16_f32 v32, v50, v51
	v_cvt_pk_bf16_f32 v33, v52, v53
	global_store_dwordx4 v[180:181], v[26:29], off offset:256
	global_store_dwordx4 v[178:179], v[30:33], off offset:256
	ds_read2_b32 v[26:27], v212 offset0:32 offset1:48
	s_waitcnt lgkmcnt(0)
	v_pk_mul_f32 v[28:29], v[68:69], v[26:27] op_sel_hi:[1,0]
	v_pk_mul_f32 v[30:31], v[66:67], v[26:27] op_sel_hi:[1,0]
	v_pk_mul_f32 v[32:33], v[72:73], v[26:27] op_sel_hi:[1,0]
	v_pk_mul_f32 v[42:43], v[70:71], v[26:27] op_sel_hi:[1,0]
	v_mov_b32_e32 v26, v27
	v_pk_fma_f32 v[28:29], v[242:243], v[28:29], v[238:239]
	v_pk_fma_f32 v[30:31], v[240:241], v[30:31], v[236:237]
	v_pk_fma_f32 v[32:33], v[246:247], v[32:33], v[250:251]
	v_pk_fma_f32 v[42:43], v[244:245], v[42:43], v[248:249]
	v_pk_mul_f32 v[44:45], v[92:93], v[26:27] op_sel_hi:[1,0]
	v_pk_mul_f32 v[50:51], v[90:91], v[26:27] op_sel_hi:[1,0]
	v_pk_mul_f32 v[52:53], v[96:97], v[26:27] op_sel_hi:[1,0]
	v_pk_mul_f32 v[64:65], v[94:95], v[26:27] op_sel_hi:[1,0]
	v_cvt_pk_bf16_f32 v26, v30, v31
	v_cvt_pk_bf16_f32 v27, v28, v29
	v_cvt_pk_bf16_f32 v28, v42, v43
	v_cvt_pk_bf16_f32 v29, v32, v33
	v_pk_fma_f32 v[30:31], v[242:243], v[44:45], v[238:239]
	v_pk_fma_f32 v[32:33], v[240:241], v[50:51], v[236:237]
	v_pk_fma_f32 v[42:43], v[246:247], v[52:53], v[250:251]
	v_pk_fma_f32 v[44:45], v[244:245], v[64:65], v[248:249]
	global_store_dwordx4 v[84:85], v[26:29], off offset:256
	s_nop 1
	v_cvt_pk_bf16_f32 v26, v32, v33
	v_cvt_pk_bf16_f32 v27, v30, v31
	v_cvt_pk_bf16_f32 v28, v44, v45
	v_cvt_pk_bf16_f32 v29, v42, v43
	global_store_dwordx4 v[82:83], v[26:29], off offset:256
	ds_read2_b32 v[26:27], v212 offset0:128 offset1:144
	s_waitcnt lgkmcnt(0)
	v_pk_mul_f32 v[30:31], v[78:79], v[26:27] op_sel_hi:[1,0]
	v_pk_mul_f32 v[28:29], v[80:81], v[26:27] op_sel_hi:[1,0]
	v_pk_mul_f32 v[32:33], v[76:77], v[26:27] op_sel_hi:[1,0]
	v_pk_mul_f32 v[42:43], v[74:75], v[26:27] op_sel_hi:[1,0]
	v_mov_b32_e32 v44, v27
	v_pk_fma_f32 v[28:29], v[242:243], v[28:29], v[238:239]
	v_pk_fma_f32 v[26:27], v[240:241], v[30:31], v[236:237]
	v_pk_fma_f32 v[30:31], v[246:247], v[32:33], v[250:251]
	v_pk_fma_f32 v[32:33], v[244:245], v[42:43], v[248:249]
	v_pk_mul_f32 v[42:43], v[56:57], v[44:45] op_sel_hi:[1,0]
	v_pk_mul_f32 v[50:51], v[54:55], v[44:45] op_sel_hi:[1,0]
	v_cvt_pk_bf16_f32 v26, v26, v27
	v_cvt_pk_bf16_f32 v27, v28, v29
	v_cvt_pk_bf16_f32 v28, v32, v33
	v_cvt_pk_bf16_f32 v29, v30, v31
	v_pk_mul_f32 v[30:31], v[48:49], v[44:45] op_sel_hi:[1,0]
	v_pk_mul_f32 v[32:33], v[46:47], v[44:45] op_sel_hi:[1,0]
	global_store_dwordx4 v[86:87], v[26:29], off offset:256
	v_pk_fma_f32 v[30:31], v[246:247], v[30:31], v[250:251]
	v_pk_fma_f32 v[32:33], v[244:245], v[32:33], v[248:249]
	v_pk_fma_f32 v[28:29], v[242:243], v[42:43], v[238:239]
	v_pk_fma_f32 v[26:27], v[240:241], v[50:51], v[236:237]
	s_nop 0
	v_cvt_pk_bf16_f32 v26, v26, v27
	v_cvt_pk_bf16_f32 v27, v28, v29
	v_cvt_pk_bf16_f32 v28, v32, v33
	v_cvt_pk_bf16_f32 v29, v30, v31
	global_store_dwordx4 v[62:63], v[26:29], off offset:256
	ds_read2_b32 v[26:27], v212 offset0:160 offset1:176
	s_waitcnt lgkmcnt(0)
	v_pk_mul_f32 v[24:25], v[24:25], v[26:27] op_sel_hi:[1,0]
	v_pk_mul_f32 v[22:23], v[22:23], v[26:27] op_sel_hi:[1,0]
	v_pk_mul_f32 v[20:21], v[20:21], v[26:27] op_sel_hi:[1,0]
	v_pk_mul_f32 v[18:19], v[18:19], v[26:27] op_sel_hi:[1,0]
	v_pk_fma_f32 v[24:25], v[242:243], v[24:25], v[238:239]
	v_pk_fma_f32 v[22:23], v[240:241], v[22:23], v[236:237]
	v_pk_fma_f32 v[28:29], v[246:247], v[20:21], v[250:251]
	v_pk_fma_f32 v[20:21], v[244:245], v[18:19], v[248:249]
	v_cvt_pk_bf16_f32 v18, v22, v23
	v_cvt_pk_bf16_f32 v19, v24, v25
	v_cvt_pk_bf16_f32 v20, v20, v21
	v_cvt_pk_bf16_f32 v21, v28, v29
	global_store_dwordx4 v[60:61], v[18:21], off offset:256
	s_nop 1
	v_mov_b32_e32 v18, v27
	v_pk_mul_f32 v[8:9], v[8:9], v[18:19] op_sel_hi:[1,0]
	v_pk_mul_f32 v[6:7], v[6:7], v[18:19] op_sel_hi:[1,0]
	v_pk_mul_f32 v[4:5], v[4:5], v[18:19] op_sel_hi:[1,0]
	v_pk_mul_f32 v[2:3], v[2:3], v[18:19] op_sel_hi:[1,0]
	v_pk_fma_f32 v[8:9], v[242:243], v[8:9], v[238:239]
	v_pk_fma_f32 v[6:7], v[240:241], v[6:7], v[236:237]
	v_pk_fma_f32 v[236:237], v[246:247], v[4:5], v[250:251]
	v_pk_fma_f32 v[4:5], v[244:245], v[2:3], v[248:249]
	v_cvt_pk_bf16_f32 v2, v6, v7
	v_cvt_pk_bf16_f32 v3, v8, v9
	v_cvt_pk_bf16_f32 v4, v4, v5
	v_cvt_pk_bf16_f32 v5, v236, v237
	global_store_dwordx4 v[58:59], v[2:5], off offset:256
	s_cbranch_vccnz .LBB0_352
	s_andn2_b64 vcc, exec, s[12:13]
	s_cbranch_vccnz .LBB0_351
	s_barrier
	s_branch .LBB0_351

.LBB0_738:
	s_ashr_i32 s39, s38, 31
	s_lshl_b64 s[16:17], s[38:39], 13
	s_mul_hi_i32 s15, s38, 0x12000
	s_mul_i32 s14, s38, 0x12000
	s_waitcnt vmcnt(0) lgkmcnt(0)
	s_barrier
	v_lshl_add_u64 v[186:187], v[166:167], 0, s[16:17]
	v_lshl_add_u64 v[192:193], v[168:169], 0, s[14:15]
	global_load_dwordx4 v[138:141], v[186:187], off
	global_load_dwordx4 v[142:145], v[192:193], off
	global_load_dwordx4 v[130:133], v[192:193], off offset:16
	global_load_dwordx4 v[134:137], v[186:187], off offset:16
	global_load_dwordx4 v[236:239], v[192:193], off offset:512
	global_load_dwordx4 v[240:243], v[186:187], off offset:512
	global_load_dwordx4 v[244:247], v[186:187], off offset:528
	global_load_dwordx4 v[248:251], v[192:193], off offset:528
	ds_read2_b32 v[196:197], v213 offset1:16
	v_lshlrev_b64 v[178:179], 12, v[178:179]
	v_lshlrev_b64 v[200:201], 12, v[180:181]
	v_lshl_add_u64 v[180:181], v[170:171], 0, v[178:179]
	v_lshl_add_u64 v[178:179], v[170:171], 0, v[200:201]
	s_waitcnt lgkmcnt(0)
	v_pk_mul_f32 v[84:85], v[84:85], v[196:197] op_sel_hi:[1,0]
	v_pk_mul_f32 v[82:83], v[82:83], v[196:197] op_sel_hi:[1,0]
	v_pk_mul_f32 v[80:81], v[80:81], v[196:197] op_sel_hi:[1,0]
	v_pk_mul_f32 v[78:79], v[78:79], v[196:197] op_sel_hi:[1,0]
	v_mov_b32_e32 v196, v197
	v_pk_mul_f32 v[112:113], v[112:113], v[196:197] op_sel_hi:[1,0]
	v_pk_mul_f32 v[110:111], v[110:111], v[196:197] op_sel_hi:[1,0]
	v_pk_mul_f32 v[108:109], v[108:109], v[196:197] op_sel_hi:[1,0]
	v_pk_mul_f32 v[106:107], v[106:107], v[196:197] op_sel_hi:[1,0]
	s_andn2_b64 vcc, exec, s[34:35]
	s_mov_b64 s[34:35], -1
	s_waitcnt vmcnt(6)
	v_pk_fma_f32 v[84:85], v[140:141], v[84:85], v[144:145]
	v_pk_fma_f32 v[82:83], v[138:139], v[82:83], v[142:143]
	s_waitcnt vmcnt(4)
	v_pk_fma_f32 v[196:197], v[136:137], v[80:81], v[132:133]
	v_pk_fma_f32 v[80:81], v[134:135], v[78:79], v[130:131]
	v_pk_fma_f32 v[112:113], v[140:141], v[112:113], v[144:145]
	v_pk_fma_f32 v[110:111], v[138:139], v[110:111], v[142:143]
	v_pk_fma_f32 v[108:109], v[136:137], v[108:109], v[132:133]
	v_pk_fma_f32 v[106:107], v[134:135], v[106:107], v[130:131]
	v_cvt_pk_bf16_f32 v78, v82, v83
	v_cvt_pk_bf16_f32 v79, v84, v85
	v_cvt_pk_bf16_f32 v80, v80, v81
	v_cvt_pk_bf16_f32 v81, v196, v197
	v_cvt_pk_bf16_f32 v82, v110, v111
	v_cvt_pk_bf16_f32 v83, v112, v113
	v_cvt_pk_bf16_f32 v84, v106, v107
	v_cvt_pk_bf16_f32 v85, v108, v109
	global_store_dwordx4 v[180:181], v[78:81], off
	global_store_dwordx4 v[178:179], v[82:85], off
	ds_read2_b32 v[82:83], v213 offset0:32 offset1:48
	v_lshlrev_b64 v[78:79], 12, v[182:183]
	v_lshlrev_b64 v[84:85], 12, v[184:185]
	v_lshl_add_u64 v[80:81], v[170:171], 0, v[78:79]
	v_lshl_add_u64 v[78:79], v[170:171], 0, v[84:85]
	s_waitcnt lgkmcnt(0)
	v_pk_mul_f32 v[84:85], v[120:121], v[82:83] op_sel_hi:[1,0]
	v_pk_mul_f32 v[106:107], v[118:119], v[82:83] op_sel_hi:[1,0]
	v_pk_mul_f32 v[108:109], v[116:117], v[82:83] op_sel_hi:[1,0]
	v_pk_mul_f32 v[110:111], v[114:115], v[82:83] op_sel_hi:[1,0]
	v_mov_b32_e32 v82, v83
	v_pk_fma_f32 v[84:85], v[140:141], v[84:85], v[144:145]
	v_pk_fma_f32 v[106:107], v[138:139], v[106:107], v[142:143]
	v_pk_fma_f32 v[108:109], v[136:137], v[108:109], v[132:133]
	v_pk_fma_f32 v[110:111], v[134:135], v[110:111], v[130:131]
	v_pk_mul_f32 v[112:113], v[128:129], v[82:83] op_sel_hi:[1,0]
	v_pk_mul_f32 v[114:115], v[126:127], v[82:83] op_sel_hi:[1,0]
	v_pk_mul_f32 v[116:117], v[124:125], v[82:83] op_sel_hi:[1,0]
	v_pk_mul_f32 v[118:119], v[122:123], v[82:83] op_sel_hi:[1,0]
	v_cvt_pk_bf16_f32 v82, v106, v107
	v_cvt_pk_bf16_f32 v83, v84, v85
	v_cvt_pk_bf16_f32 v84, v110, v111
	v_cvt_pk_bf16_f32 v85, v108, v109
	v_pk_fma_f32 v[106:107], v[140:141], v[112:113], v[144:145]
	v_pk_fma_f32 v[108:109], v[138:139], v[114:115], v[142:143]
	v_pk_fma_f32 v[110:111], v[136:137], v[116:117], v[132:133]
	v_pk_fma_f32 v[112:113], v[134:135], v[118:119], v[130:131]
	global_store_dwordx4 v[80:81], v[82:85], off
	s_nop 1
	v_cvt_pk_bf16_f32 v82, v108, v109
	v_cvt_pk_bf16_f32 v83, v106, v107
	v_cvt_pk_bf16_f32 v84, v112, v113
	v_cvt_pk_bf16_f32 v85, v110, v111
	global_store_dwordx4 v[78:79], v[82:85], off
	ds_read2_b32 v[84:85], v213 offset0:128 offset1:144
	s_waitcnt lgkmcnt(0)
	v_pk_mul_f32 v[104:105], v[104:105], v[84:85] op_sel_hi:[1,0]
	v_pk_mul_f32 v[102:103], v[102:103], v[84:85] op_sel_hi:[1,0]
	v_pk_mul_f32 v[100:101], v[100:101], v[84:85] op_sel_hi:[1,0]
	v_pk_mul_f32 v[98:99], v[98:99], v[84:85] op_sel_hi:[1,0]
	v_mov_b32_e32 v84, v85
	v_lshlrev_b64 v[82:83], 12, v[188:189]
	v_pk_fma_f32 v[104:105], v[140:141], v[104:105], v[144:145]
	v_pk_fma_f32 v[102:103], v[138:139], v[102:103], v[142:143]
	v_pk_fma_f32 v[100:101], v[136:137], v[100:101], v[132:133]
	v_pk_fma_f32 v[98:99], v[134:135], v[98:99], v[130:131]
	v_pk_mul_f32 v[66:67], v[66:67], v[84:85] op_sel_hi:[1,0]
	v_lshl_add_u64 v[82:83], v[170:171], 0, v[82:83]
	v_pk_mul_f32 v[68:69], v[68:69], v[84:85] op_sel_hi:[1,0]
	v_pk_mul_f32 v[106:107], v[60:61], v[84:85] op_sel_hi:[1,0]
	v_pk_mul_f32 v[84:85], v[58:59], v[84:85] op_sel_hi:[1,0]
	v_cvt_pk_bf16_f32 v58, v102, v103
	v_cvt_pk_bf16_f32 v59, v104, v105
	v_cvt_pk_bf16_f32 v60, v98, v99
	v_cvt_pk_bf16_f32 v61, v100, v101
	v_pk_fma_f32 v[66:67], v[138:139], v[66:67], v[142:143]
	v_pk_fma_f32 v[68:69], v[140:141], v[68:69], v[144:145]
	v_pk_fma_f32 v[98:99], v[136:137], v[106:107], v[132:133]
	v_pk_fma_f32 v[84:85], v[134:135], v[84:85], v[130:131]
	global_store_dwordx4 v[82:83], v[58:61], off
	s_nop 1
	v_cvt_pk_bf16_f32 v58, v66, v67
	v_lshlrev_b64 v[66:67], 12, v[190:191]
	v_cvt_pk_bf16_f32 v59, v68, v69
	v_cvt_pk_bf16_f32 v60, v84, v85
	v_cvt_pk_bf16_f32 v61, v98, v99
	v_lshl_add_u64 v[66:67], v[170:171], 0, v[66:67]
	global_store_dwordx4 v[66:67], v[58:61], off
	ds_read2_b32 v[58:59], v213 offset0:160 offset1:176
	s_waitcnt lgkmcnt(0)
	v_pk_mul_f32 v[38:39], v[38:39], v[58:59] op_sel_hi:[1,0]
	v_pk_mul_f32 v[40:41], v[40:41], v[58:59] op_sel_hi:[1,0]
	v_pk_fma_f32 v[38:39], v[138:139], v[38:39], v[142:143]
	v_pk_mul_f32 v[36:37], v[36:37], v[58:59] op_sel_hi:[1,0]
	v_pk_mul_f32 v[34:35], v[34:35], v[58:59] op_sel_hi:[1,0]
	v_pk_fma_f32 v[40:41], v[140:141], v[40:41], v[144:145]
	v_pk_fma_f32 v[60:61], v[136:137], v[36:37], v[132:133]
	v_pk_fma_f32 v[36:37], v[134:135], v[34:35], v[130:131]
	v_cvt_pk_bf16_f32 v34, v38, v39
	v_lshlrev_b64 v[38:39], 12, v[194:195]
	v_cvt_pk_bf16_f32 v35, v40, v41
	v_cvt_pk_bf16_f32 v36, v36, v37
	v_cvt_pk_bf16_f32 v37, v60, v61
	v_lshl_add_u64 v[60:61], v[170:171], 0, v[38:39]
	global_store_dwordx4 v[60:61], v[34:37], off
	s_nop 1
	v_mov_b32_e32 v34, v59
	v_pk_mul_f32 v[14:15], v[14:15], v[34:35] op_sel_hi:[1,0]
	v_pk_mul_f32 v[16:17], v[16:17], v[34:35] op_sel_hi:[1,0]
	v_pk_fma_f32 v[14:15], v[138:139], v[14:15], v[142:143]
	v_pk_mul_f32 v[12:13], v[12:13], v[34:35] op_sel_hi:[1,0]
	v_pk_mul_f32 v[10:11], v[10:11], v[34:35] op_sel_hi:[1,0]
	v_pk_fma_f32 v[16:17], v[140:141], v[16:17], v[144:145]
	v_pk_fma_f32 v[34:35], v[136:137], v[12:13], v[132:133]
	v_pk_fma_f32 v[12:13], v[134:135], v[10:11], v[130:131]
	v_cvt_pk_bf16_f32 v10, v14, v15
	v_lshlrev_b64 v[14:15], 12, v[198:199]
	v_cvt_pk_bf16_f32 v11, v16, v17
	v_cvt_pk_bf16_f32 v12, v12, v13
	v_cvt_pk_bf16_f32 v13, v34, v35
	v_lshl_add_u64 v[58:59], v[170:171], 0, v[14:15]
	global_store_dwordx4 v[58:59], v[10:13], off
	ds_read2_b32 v[68:69], v213 offset1:16
	s_waitcnt lgkmcnt(0)
	v_pk_mul_f32 v[24:25], v[24:25], v[68:69] op_sel_hi:[1,0]
	v_pk_mul_f32 v[22:23], v[22:23], v[68:69] op_sel_hi:[1,0]
	v_pk_mul_f32 v[28:29], v[28:29], v[68:69] op_sel_hi:[1,0]
	v_pk_mul_f32 v[26:27], v[26:27], v[68:69] op_sel_hi:[1,0]
	v_mov_b32_e32 v68, v69
	v_pk_mul_f32 v[44:45], v[44:45], v[68:69] op_sel_hi:[1,0]
	v_pk_mul_f32 v[42:43], v[42:43], v[68:69] op_sel_hi:[1,0]
	v_pk_mul_f32 v[48:49], v[48:49], v[68:69] op_sel_hi:[1,0]
	v_pk_mul_f32 v[46:47], v[46:47], v[68:69] op_sel_hi:[1,0]
	s_waitcnt vmcnt(8)
	v_pk_fma_f32 v[24:25], v[242:243], v[24:25], v[238:239]
	v_pk_fma_f32 v[22:23], v[240:241], v[22:23], v[236:237]
	s_waitcnt vmcnt(8)
	v_pk_fma_f32 v[28:29], v[246:247], v[28:29], v[250:251]
	v_pk_fma_f32 v[26:27], v[244:245], v[26:27], v[248:249]
	v_pk_fma_f32 v[44:45], v[242:243], v[44:45], v[238:239]
	v_pk_fma_f32 v[42:43], v[240:241], v[42:43], v[236:237]
	v_pk_fma_f32 v[48:49], v[246:247], v[48:49], v[250:251]
	v_pk_fma_f32 v[46:47], v[244:245], v[46:47], v[248:249]
	v_cvt_pk_bf16_f32 v22, v22, v23
	v_cvt_pk_bf16_f32 v23, v24, v25
	v_cvt_pk_bf16_f32 v24, v26, v27
	v_cvt_pk_bf16_f32 v25, v28, v29
	v_cvt_pk_bf16_f32 v26, v42, v43
	v_cvt_pk_bf16_f32 v27, v44, v45
	v_cvt_pk_bf16_f32 v28, v46, v47
	v_cvt_pk_bf16_f32 v29, v48, v49
	global_store_dwordx4 v[180:181], v[22:25], off offset:256
	global_store_dwordx4 v[178:179], v[26:29], off offset:256
	ds_read2_b32 v[22:23], v213 offset0:32 offset1:48
	s_waitcnt lgkmcnt(0)
	v_pk_mul_f32 v[24:25], v[64:65], v[22:23] op_sel_hi:[1,0]
	v_pk_mul_f32 v[26:27], v[62:63], v[22:23] op_sel_hi:[1,0]
	v_pk_mul_f32 v[28:29], v[72:73], v[22:23] op_sel_hi:[1,0]
	v_pk_mul_f32 v[42:43], v[70:71], v[22:23] op_sel_hi:[1,0]
	v_mov_b32_e32 v22, v23
	v_pk_fma_f32 v[24:25], v[242:243], v[24:25], v[238:239]
	v_pk_fma_f32 v[26:27], v[240:241], v[26:27], v[236:237]
	v_pk_fma_f32 v[28:29], v[246:247], v[28:29], v[250:251]
	v_pk_fma_f32 v[42:43], v[244:245], v[42:43], v[248:249]
	v_pk_mul_f32 v[44:45], v[92:93], v[22:23] op_sel_hi:[1,0]
	v_pk_mul_f32 v[46:47], v[90:91], v[22:23] op_sel_hi:[1,0]
	v_pk_mul_f32 v[48:49], v[96:97], v[22:23] op_sel_hi:[1,0]
	v_pk_mul_f32 v[62:63], v[94:95], v[22:23] op_sel_hi:[1,0]
	v_cvt_pk_bf16_f32 v22, v26, v27
	v_cvt_pk_bf16_f32 v23, v24, v25
	v_cvt_pk_bf16_f32 v24, v42, v43
	v_cvt_pk_bf16_f32 v25, v28, v29
	v_pk_fma_f32 v[26:27], v[242:243], v[44:45], v[238:239]
	v_pk_fma_f32 v[28:29], v[240:241], v[46:47], v[236:237]
	v_pk_fma_f32 v[42:43], v[246:247], v[48:49], v[250:251]
	v_pk_fma_f32 v[44:45], v[244:245], v[62:63], v[248:249]
	global_store_dwordx4 v[80:81], v[22:25], off offset:256
	s_nop 1
	v_cvt_pk_bf16_f32 v22, v28, v29
	v_cvt_pk_bf16_f32 v23, v26, v27
	v_cvt_pk_bf16_f32 v24, v44, v45
	v_cvt_pk_bf16_f32 v25, v42, v43
	global_store_dwordx4 v[78:79], v[22:25], off offset:256
	ds_read2_b32 v[22:23], v213 offset0:128 offset1:144
	s_waitcnt lgkmcnt(0)
	v_pk_mul_f32 v[26:27], v[86:87], v[22:23] op_sel_hi:[1,0]
	v_pk_mul_f32 v[24:25], v[88:89], v[22:23] op_sel_hi:[1,0]
	v_pk_mul_f32 v[28:29], v[76:77], v[22:23] op_sel_hi:[1,0]
	v_pk_mul_f32 v[42:43], v[74:75], v[22:23] op_sel_hi:[1,0]
	v_mov_b32_e32 v44, v23
	v_pk_fma_f32 v[24:25], v[242:243], v[24:25], v[238:239]
	v_pk_fma_f32 v[22:23], v[240:241], v[26:27], v[236:237]
	v_pk_fma_f32 v[26:27], v[246:247], v[28:29], v[250:251]
	v_pk_fma_f32 v[28:29], v[244:245], v[42:43], v[248:249]
	v_pk_mul_f32 v[42:43], v[56:57], v[44:45] op_sel_hi:[1,0]
	v_pk_mul_f32 v[46:47], v[54:55], v[44:45] op_sel_hi:[1,0]
	v_cvt_pk_bf16_f32 v22, v22, v23
	v_cvt_pk_bf16_f32 v23, v24, v25
	v_cvt_pk_bf16_f32 v24, v28, v29
	v_cvt_pk_bf16_f32 v25, v26, v27
	v_pk_mul_f32 v[26:27], v[52:53], v[44:45] op_sel_hi:[1,0]
	v_pk_mul_f32 v[28:29], v[50:51], v[44:45] op_sel_hi:[1,0]
	global_store_dwordx4 v[82:83], v[22:25], off offset:256
	v_pk_fma_f32 v[26:27], v[246:247], v[26:27], v[250:251]
	v_pk_fma_f32 v[28:29], v[244:245], v[28:29], v[248:249]
	v_pk_fma_f32 v[24:25], v[242:243], v[42:43], v[238:239]
	v_pk_fma_f32 v[22:23], v[240:241], v[46:47], v[236:237]
	s_nop 0
	v_cvt_pk_bf16_f32 v22, v22, v23
	v_cvt_pk_bf16_f32 v23, v24, v25
	v_cvt_pk_bf16_f32 v24, v28, v29
	v_cvt_pk_bf16_f32 v25, v26, v27
	global_store_dwordx4 v[66:67], v[22:25], off offset:256
	ds_read2_b32 v[22:23], v213 offset0:160 offset1:176
	s_waitcnt lgkmcnt(0)
	v_pk_mul_f32 v[26:27], v[30:31], v[22:23] op_sel_hi:[1,0]
	v_pk_mul_f32 v[24:25], v[32:33], v[22:23] op_sel_hi:[1,0]
	v_pk_mul_f32 v[20:21], v[20:21], v[22:23] op_sel_hi:[1,0]
	v_pk_mul_f32 v[18:19], v[18:19], v[22:23] op_sel_hi:[1,0]
	v_pk_fma_f32 v[24:25], v[242:243], v[24:25], v[238:239]
	v_pk_fma_f32 v[26:27], v[240:241], v[26:27], v[236:237]
	v_pk_fma_f32 v[28:29], v[246:247], v[20:21], v[250:251]
	v_pk_fma_f32 v[20:21], v[244:245], v[18:19], v[248:249]
	v_cvt_pk_bf16_f32 v18, v26, v27
	v_cvt_pk_bf16_f32 v19, v24, v25
	v_cvt_pk_bf16_f32 v20, v20, v21
	v_cvt_pk_bf16_f32 v21, v28, v29
	global_store_dwordx4 v[60:61], v[18:21], off offset:256
	s_nop 1
	v_mov_b32_e32 v18, v23
	v_pk_mul_f32 v[8:9], v[8:9], v[18:19] op_sel_hi:[1,0]
	v_pk_mul_f32 v[6:7], v[6:7], v[18:19] op_sel_hi:[1,0]
	v_pk_mul_f32 v[4:5], v[4:5], v[18:19] op_sel_hi:[1,0]
	v_pk_mul_f32 v[2:3], v[2:3], v[18:19] op_sel_hi:[1,0]
	v_pk_fma_f32 v[8:9], v[242:243], v[8:9], v[238:239]
	v_pk_fma_f32 v[6:7], v[240:241], v[6:7], v[236:237]
	v_pk_fma_f32 v[236:237], v[246:247], v[4:5], v[250:251]
	v_pk_fma_f32 v[4:5], v[244:245], v[2:3], v[248:249]
	v_cvt_pk_bf16_f32 v2, v6, v7
	v_cvt_pk_bf16_f32 v3, v8, v9
	v_cvt_pk_bf16_f32 v4, v4, v5
	v_cvt_pk_bf16_f32 v5, v236, v237
	global_store_dwordx4 v[58:59], v[2:5], off offset:256
	s_cbranch_vccnz .LBB0_697
	s_andn2_b64 vcc, exec, s[24:25]
	s_cbranch_vccnz .LBB0_696
	s_barrier
	s_branch .LBB0_696

.LBB0_916:
	s_lshl_b64 s[34:35], s[36:37], 13
	s_waitcnt vmcnt(0) lgkmcnt(0)
	s_barrier
	v_lshl_add_u64 v[202:203], v[166:167], 0, s[34:35]
	v_lshl_add_u64 v[204:205], v[168:169], 0, s[40:41]
	global_load_dwordx4 v[138:141], v[202:203], off
	global_load_dwordx4 v[142:145], v[204:205], off
	global_load_dwordx4 v[130:133], v[204:205], off offset:16
	global_load_dwordx4 v[134:137], v[202:203], off offset:16
	ds_read2_b32 v[208:209], v219 offset1:16
	v_lshlrev_b64 v[184:185], 12, v[184:185]
	v_lshlrev_b64 v[186:187], 12, v[186:187]
	v_lshl_add_u64 v[206:207], v[170:171], 0, v[184:185]
	v_lshl_add_u64 v[200:201], v[170:171], 0, v[186:187]
	s_waitcnt lgkmcnt(0)
	v_pk_mul_f32 v[210:211], v[32:33], v[208:209] op_sel_hi:[1,0]
	v_pk_mul_f32 v[212:213], v[30:31], v[208:209] op_sel_hi:[1,0]
	v_pk_mul_f32 v[214:215], v[28:29], v[208:209] op_sel_hi:[1,0]
	v_pk_mul_f32 v[228:229], v[26:27], v[208:209] op_sel_hi:[1,0]
	v_mov_b32_e32 v208, v209
	v_pk_mul_f32 v[230:231], v[48:49], v[208:209] op_sel_hi:[1,0]
	v_pk_mul_f32 v[232:233], v[46:47], v[208:209] op_sel_hi:[1,0]
	v_pk_mul_f32 v[234:235], v[44:45], v[208:209] op_sel_hi:[1,0]
	v_pk_mul_f32 v[208:209], v[42:43], v[208:209] op_sel_hi:[1,0]
	v_lshlrev_b64 v[188:189], 12, v[188:189]
	v_lshlrev_b64 v[190:191], 12, v[190:191]
	v_lshlrev_b64 v[192:193], 12, v[192:193]
	v_lshlrev_b64 v[194:195], 12, v[194:195]
	v_lshlrev_b64 v[196:197], 12, v[196:197]
	s_lshl_b64 s[14:15], s[36:37], 14
	s_andn2_b64 vcc, exec, s[30:31]
	s_mov_b64 s[30:31], -1
	s_waitcnt vmcnt(2)
	v_pk_fma_f32 v[210:211], v[140:141], v[210:211], v[144:145]
	v_pk_fma_f32 v[212:213], v[138:139], v[212:213], v[142:143]
	s_waitcnt vmcnt(0)
	v_pk_fma_f32 v[214:215], v[136:137], v[214:215], v[132:133]
	v_pk_fma_f32 v[228:229], v[134:135], v[228:229], v[130:131]
	v_pk_fma_f32 v[230:231], v[140:141], v[230:231], v[144:145]
	v_pk_fma_f32 v[232:233], v[138:139], v[232:233], v[142:143]
	v_pk_fma_f32 v[234:235], v[136:137], v[234:235], v[132:133]
	v_pk_fma_f32 v[236:237], v[134:135], v[208:209], v[130:131]
	v_cvt_pk_bf16_f32 v208, v212, v213
	v_cvt_pk_bf16_f32 v209, v210, v211
	v_cvt_pk_bf16_f32 v210, v228, v229
	v_cvt_pk_bf16_f32 v211, v214, v215
	v_cvt_pk_bf16_f32 v212, v232, v233
	v_cvt_pk_bf16_f32 v213, v230, v231
	v_cvt_pk_bf16_f32 v214, v236, v237
	v_cvt_pk_bf16_f32 v215, v234, v235
	global_store_dwordx4 v[206:207], v[208:211], off
	global_store_dwordx4 v[200:201], v[212:215], off
	ds_read2_b32 v[212:213], v219 offset0:32 offset1:48
	v_lshl_add_u64 v[210:211], v[170:171], 0, v[188:189]
	v_lshl_add_u64 v[208:209], v[170:171], 0, v[190:191]
	s_waitcnt lgkmcnt(0)
	v_pk_mul_f32 v[214:215], v[64:65], v[212:213] op_sel_hi:[1,0]
	v_pk_mul_f32 v[228:229], v[62:63], v[212:213] op_sel_hi:[1,0]
	v_pk_mul_f32 v[230:231], v[60:61], v[212:213] op_sel_hi:[1,0]
	v_pk_mul_f32 v[232:233], v[58:59], v[212:213] op_sel_hi:[1,0]
	v_mov_b32_e32 v212, v213
	v_pk_fma_f32 v[214:215], v[140:141], v[214:215], v[144:145]
	v_pk_fma_f32 v[228:229], v[138:139], v[228:229], v[142:143]
	v_pk_fma_f32 v[230:231], v[136:137], v[230:231], v[132:133]
	v_pk_fma_f32 v[232:233], v[134:135], v[232:233], v[130:131]
	v_pk_mul_f32 v[234:235], v[96:97], v[212:213] op_sel_hi:[1,0]
	v_pk_mul_f32 v[236:237], v[94:95], v[212:213] op_sel_hi:[1,0]
	v_pk_mul_f32 v[238:239], v[92:93], v[212:213] op_sel_hi:[1,0]
	v_pk_mul_f32 v[240:241], v[90:91], v[212:213] op_sel_hi:[1,0]
	v_cvt_pk_bf16_f32 v212, v228, v229
	v_cvt_pk_bf16_f32 v213, v214, v215
	v_cvt_pk_bf16_f32 v214, v232, v233
	v_cvt_pk_bf16_f32 v215, v230, v231
	v_pk_fma_f32 v[228:229], v[140:141], v[234:235], v[144:145]
	v_pk_fma_f32 v[230:231], v[138:139], v[236:237], v[142:143]
	v_pk_fma_f32 v[232:233], v[136:137], v[238:239], v[132:133]
	v_pk_fma_f32 v[234:235], v[134:135], v[240:241], v[130:131]
	global_store_dwordx4 v[210:211], v[212:215], off
	s_nop 1
	v_cvt_pk_bf16_f32 v212, v230, v231
	v_cvt_pk_bf16_f32 v213, v228, v229
	v_cvt_pk_bf16_f32 v214, v234, v235
	v_cvt_pk_bf16_f32 v215, v232, v233
	global_store_dwordx4 v[208:209], v[212:215], off
	ds_read2_b32 v[214:215], v219 offset0:128 offset1:144
	s_waitcnt lgkmcnt(0)
	v_pk_mul_f32 v[228:229], v[116:117], v[214:215] op_sel_hi:[1,0]
	v_pk_mul_f32 v[230:231], v[114:115], v[214:215] op_sel_hi:[1,0]
	v_pk_mul_f32 v[232:233], v[112:113], v[214:215] op_sel_hi:[1,0]
	v_pk_mul_f32 v[234:235], v[110:111], v[214:215] op_sel_hi:[1,0]
	v_mov_b32_e32 v214, v215
	v_pk_fma_f32 v[236:237], v[140:141], v[228:229], v[144:145]
	v_pk_fma_f32 v[228:229], v[138:139], v[230:231], v[142:143]
	v_pk_fma_f32 v[232:233], v[136:137], v[232:233], v[132:133]
	v_pk_fma_f32 v[230:231], v[134:135], v[234:235], v[130:131]
	v_pk_mul_f32 v[234:235], v[128:129], v[214:215] op_sel_hi:[1,0]
	v_pk_mul_f32 v[238:239], v[126:127], v[214:215] op_sel_hi:[1,0]
	v_pk_mul_f32 v[240:241], v[124:125], v[214:215] op_sel_hi:[1,0]
	v_pk_mul_f32 v[214:215], v[122:123], v[214:215] op_sel_hi:[1,0]
	v_lshl_add_u64 v[212:213], v[170:171], 0, v[192:193]
	v_cvt_pk_bf16_f32 v228, v228, v229
	v_cvt_pk_bf16_f32 v229, v236, v237
	v_cvt_pk_bf16_f32 v230, v230, v231
	v_cvt_pk_bf16_f32 v231, v232, v233
	v_pk_fma_f32 v[232:233], v[140:141], v[234:235], v[144:145]
	v_pk_fma_f32 v[234:235], v[138:139], v[238:239], v[142:143]
	v_pk_fma_f32 v[236:237], v[136:137], v[240:241], v[132:133]
	v_pk_fma_f32 v[214:215], v[134:135], v[214:215], v[130:131]
	global_store_dwordx4 v[212:213], v[228:231], off
	s_nop 1
	v_cvt_pk_bf16_f32 v228, v234, v235
	v_cvt_pk_bf16_f32 v229, v232, v233
	v_cvt_pk_bf16_f32 v230, v214, v215
	v_cvt_pk_bf16_f32 v231, v236, v237
	v_lshl_add_u64 v[214:215], v[170:171], 0, v[194:195]
	global_store_dwordx4 v[214:215], v[228:231], off
	ds_read2_b32 v[232:233], v219 offset0:160 offset1:176
	s_waitcnt lgkmcnt(0)
	v_pk_mul_f32 v[234:235], v[108:109], v[232:233] op_sel_hi:[1,0]
	v_pk_mul_f32 v[228:229], v[120:121], v[232:233] op_sel_hi:[1,0]
	v_pk_mul_f32 v[230:231], v[118:119], v[232:233] op_sel_hi:[1,0]
	v_pk_fma_f32 v[236:237], v[140:141], v[228:229], v[144:145]
	v_pk_fma_f32 v[228:229], v[138:139], v[230:231], v[142:143]
	v_pk_mul_f32 v[230:231], v[106:107], v[232:233] op_sel_hi:[1,0]
	v_pk_fma_f32 v[234:235], v[136:137], v[234:235], v[132:133]
	v_pk_fma_f32 v[230:231], v[134:135], v[230:231], v[130:131]
	v_cvt_pk_bf16_f32 v228, v228, v229
	v_cvt_pk_bf16_f32 v229, v236, v237
	v_cvt_pk_bf16_f32 v230, v230, v231
	v_cvt_pk_bf16_f32 v231, v234, v235
	v_lshl_add_u64 v[236:237], v[170:171], 0, v[196:197]
	global_store_dwordx4 v[236:237], v[228:231], off
	s_nop 1
	v_mov_b32_e32 v228, v233
	v_pk_mul_f32 v[230:231], v[80:81], v[228:229] op_sel_hi:[1,0]
	v_pk_mul_f32 v[232:233], v[78:79], v[228:229] op_sel_hi:[1,0]
	v_pk_fma_f32 v[140:141], v[140:141], v[230:231], v[144:145]
	v_pk_mul_f32 v[144:145], v[74:75], v[228:229] op_sel_hi:[1,0]
	v_pk_fma_f32 v[138:139], v[138:139], v[232:233], v[142:143]
	v_pk_mul_f32 v[142:143], v[76:77], v[228:229] op_sel_hi:[1,0]
	v_pk_fma_f32 v[130:131], v[134:135], v[144:145], v[130:131]
	v_pk_fma_f32 v[136:137], v[136:137], v[142:143], v[132:133]
	v_cvt_pk_bf16_f32 v134, v130, v131
	v_lshlrev_b64 v[130:131], 12, v[198:199]
	v_cvt_pk_bf16_f32 v132, v138, v139
	v_cvt_pk_bf16_f32 v133, v140, v141
	v_cvt_pk_bf16_f32 v135, v136, v137
	v_lshl_add_u64 v[144:145], v[170:171], 0, v[130:131]
	global_store_dwordx4 v[144:145], v[132:135], off
	global_load_dwordx4 v[132:135], v[204:205], off offset:512
	global_load_dwordx4 v[136:139], v[202:203], off offset:512
	global_load_dwordx4 v[140:143], v[202:203], off offset:528
	s_nop 0
	global_load_dwordx4 v[202:205], v[204:205], off offset:528
	ds_read2_b32 v[198:199], v219 offset1:16
	s_waitcnt lgkmcnt(0)
	v_pk_mul_f32 v[228:229], v[4:5], v[198:199] op_sel_hi:[1,0]
	v_pk_mul_f32 v[230:231], v[2:3], v[198:199] op_sel_hi:[1,0]
	v_pk_mul_f32 v[232:233], v[8:9], v[198:199] op_sel_hi:[1,0]
	v_pk_mul_f32 v[234:235], v[6:7], v[198:199] op_sel_hi:[1,0]
	v_mov_b32_e32 v198, v199
	v_pk_mul_f32 v[238:239], v[12:13], v[198:199] op_sel_hi:[1,0]
	v_pk_mul_f32 v[240:241], v[10:11], v[198:199] op_sel_hi:[1,0]
	v_pk_mul_f32 v[242:243], v[16:17], v[198:199] op_sel_hi:[1,0]
	v_pk_mul_f32 v[198:199], v[14:15], v[198:199] op_sel_hi:[1,0]
	s_waitcnt vmcnt(2)
	v_pk_fma_f32 v[244:245], v[138:139], v[228:229], v[134:135]
	v_pk_fma_f32 v[228:229], v[136:137], v[230:231], v[132:133]
	s_waitcnt vmcnt(0)
	v_pk_fma_f32 v[232:233], v[142:143], v[232:233], v[204:205]
	v_pk_fma_f32 v[230:231], v[140:141], v[234:235], v[202:203]
	v_pk_fma_f32 v[234:235], v[138:139], v[238:239], v[134:135]
	v_pk_fma_f32 v[238:239], v[136:137], v[240:241], v[132:133]
	v_pk_fma_f32 v[240:241], v[142:143], v[242:243], v[204:205]
	v_pk_fma_f32 v[198:199], v[140:141], v[198:199], v[202:203]
	v_cvt_pk_bf16_f32 v228, v228, v229
	v_cvt_pk_bf16_f32 v229, v244, v245
	v_cvt_pk_bf16_f32 v230, v230, v231
	v_cvt_pk_bf16_f32 v231, v232, v233
	v_cvt_pk_bf16_f32 v232, v238, v239
	v_cvt_pk_bf16_f32 v233, v234, v235
	v_cvt_pk_bf16_f32 v234, v198, v199
	v_cvt_pk_bf16_f32 v235, v240, v241
	global_store_dwordx4 v[206:207], v[228:231], off offset:256
	global_store_dwordx4 v[200:201], v[232:235], off offset:256
	ds_read2_b32 v[198:199], v219 offset0:32 offset1:48
	s_waitcnt lgkmcnt(0)
	v_pk_mul_f32 v[200:201], v[20:21], v[198:199] op_sel_hi:[1,0]
	v_pk_mul_f32 v[206:207], v[18:19], v[198:199] op_sel_hi:[1,0]
	v_pk_mul_f32 v[228:229], v[24:25], v[198:199] op_sel_hi:[1,0]
	v_pk_mul_f32 v[230:231], v[22:23], v[198:199] op_sel_hi:[1,0]
	v_mov_b32_e32 v198, v199
	v_pk_fma_f32 v[200:201], v[138:139], v[200:201], v[134:135]
	v_pk_fma_f32 v[206:207], v[136:137], v[206:207], v[132:133]
	v_pk_fma_f32 v[228:229], v[142:143], v[228:229], v[204:205]
	v_pk_fma_f32 v[230:231], v[140:141], v[230:231], v[202:203]
	v_pk_mul_f32 v[232:233], v[36:37], v[198:199] op_sel_hi:[1,0]
	v_pk_mul_f32 v[234:235], v[34:35], v[198:199] op_sel_hi:[1,0]
	v_pk_mul_f32 v[238:239], v[40:41], v[198:199] op_sel_hi:[1,0]
	v_pk_mul_f32 v[240:241], v[38:39], v[198:199] op_sel_hi:[1,0]
	v_cvt_pk_bf16_f32 v198, v206, v207
	v_cvt_pk_bf16_f32 v199, v200, v201
	v_cvt_pk_bf16_f32 v200, v230, v231
	v_cvt_pk_bf16_f32 v201, v228, v229
	v_pk_fma_f32 v[206:207], v[138:139], v[232:233], v[134:135]
	v_pk_fma_f32 v[228:229], v[136:137], v[234:235], v[132:133]
	v_pk_fma_f32 v[230:231], v[142:143], v[238:239], v[204:205]
	v_pk_fma_f32 v[232:233], v[140:141], v[240:241], v[202:203]
	global_store_dwordx4 v[210:211], v[198:201], off offset:256
	s_nop 1
	v_cvt_pk_bf16_f32 v198, v228, v229
	v_cvt_pk_bf16_f32 v199, v206, v207
	v_cvt_pk_bf16_f32 v200, v232, v233
	v_cvt_pk_bf16_f32 v201, v230, v231
	global_store_dwordx4 v[208:209], v[198:201], off offset:256
	ds_read2_b32 v[198:199], v219 offset0:128 offset1:144
	s_waitcnt lgkmcnt(0)
	v_pk_mul_f32 v[206:207], v[50:51], v[198:199] op_sel_hi:[1,0]
	v_pk_mul_f32 v[200:201], v[52:53], v[198:199] op_sel_hi:[1,0]
	v_pk_mul_f32 v[208:209], v[56:57], v[198:199] op_sel_hi:[1,0]
	v_pk_mul_f32 v[210:211], v[54:55], v[198:199] op_sel_hi:[1,0]
	v_mov_b32_e32 v228, v199
	v_pk_fma_f32 v[200:201], v[138:139], v[200:201], v[134:135]
	v_pk_fma_f32 v[198:199], v[136:137], v[206:207], v[132:133]
	v_pk_fma_f32 v[206:207], v[142:143], v[208:209], v[204:205]
	v_pk_fma_f32 v[208:209], v[140:141], v[210:211], v[202:203]
	v_cvt_pk_bf16_f32 v198, v198, v199
	v_cvt_pk_bf16_f32 v199, v200, v201
	v_cvt_pk_bf16_f32 v200, v208, v209
	v_cvt_pk_bf16_f32 v201, v206, v207
	v_pk_mul_f32 v[210:211], v[84:85], v[228:229] op_sel_hi:[1,0]
	v_pk_mul_f32 v[230:231], v[82:83], v[228:229] op_sel_hi:[1,0]
	global_store_dwordx4 v[212:213], v[198:201], off offset:256
	v_pk_fma_f32 v[206:207], v[138:139], v[210:211], v[134:135]
	v_pk_fma_f32 v[208:209], v[136:137], v[230:231], v[132:133]
	v_pk_mul_f32 v[198:199], v[88:89], v[228:229] op_sel_hi:[1,0]
	v_pk_mul_f32 v[200:201], v[86:87], v[228:229] op_sel_hi:[1,0]
	v_pk_fma_f32 v[210:211], v[142:143], v[198:199], v[204:205]
	v_pk_fma_f32 v[200:201], v[140:141], v[200:201], v[202:203]
	v_cvt_pk_bf16_f32 v198, v208, v209
	v_cvt_pk_bf16_f32 v199, v206, v207
	v_cvt_pk_bf16_f32 v200, v200, v201
	v_cvt_pk_bf16_f32 v201, v210, v211
	global_store_dwordx4 v[214:215], v[198:201], off offset:256
	ds_read2_b32 v[206:207], v219 offset0:160 offset1:176
	s_waitcnt lgkmcnt(0)
	v_pk_mul_f32 v[210:211], v[98:99], v[206:207] op_sel_hi:[1,0]
	v_pk_mul_f32 v[198:199], v[104:105], v[206:207] op_sel_hi:[1,0]
	v_pk_mul_f32 v[200:201], v[102:103], v[206:207] op_sel_hi:[1,0]
	v_pk_fma_f32 v[208:209], v[138:139], v[198:199], v[134:135]
	v_pk_fma_f32 v[198:199], v[136:137], v[200:201], v[132:133]
	v_pk_mul_f32 v[200:201], v[100:101], v[206:207] op_sel_hi:[1,0]
	v_cvt_pk_bf16_f32 v198, v198, v199
	v_pk_fma_f32 v[212:213], v[142:143], v[200:201], v[204:205]
	v_pk_fma_f32 v[200:201], v[140:141], v[210:211], v[202:203]
	v_cvt_pk_bf16_f32 v199, v208, v209
	v_cvt_pk_bf16_f32 v200, v200, v201
	v_cvt_pk_bf16_f32 v201, v212, v213
	global_store_dwordx4 v[236:237], v[198:201], off offset:256
	s_nop 1
	v_mov_b32_e32 v198, v207
	v_pk_mul_f32 v[200:201], v[72:73], v[198:199] op_sel_hi:[1,0]
	v_pk_mul_f32 v[206:207], v[70:71], v[198:199] op_sel_hi:[1,0]
	v_pk_fma_f32 v[134:135], v[138:139], v[200:201], v[134:135]
	v_pk_fma_f32 v[132:133], v[136:137], v[206:207], v[132:133]
	v_pk_mul_f32 v[136:137], v[68:69], v[198:199] op_sel_hi:[1,0]
	v_pk_mul_f32 v[138:139], v[66:67], v[198:199] op_sel_hi:[1,0]
	v_pk_fma_f32 v[136:137], v[142:143], v[136:137], v[204:205]
	v_pk_fma_f32 v[138:139], v[140:141], v[138:139], v[202:203]
	v_cvt_pk_bf16_f32 v132, v132, v133
	v_cvt_pk_bf16_f32 v133, v134, v135
	v_cvt_pk_bf16_f32 v134, v138, v139
	v_cvt_pk_bf16_f32 v135, v136, v137
	global_store_dwordx4 v[144:145], v[132:135], off offset:256
	v_lshl_add_u64 v[204:205], v[174:175], 0, s[14:15]
	v_lshl_add_u64 v[202:203], v[172:173], 0, s[34:35]
	global_load_dwordx4 v[134:137], v[204:205], off
	global_load_dwordx4 v[138:141], v[202:203], off
	global_load_dwordx4 v[142:145], v[202:203], off offset:16
	global_load_dwordx4 v[198:201], v[204:205], off offset:16
	global_load_dwordx4 v[236:239], v[204:205], off offset:512
	global_load_dwordx4 v[240:243], v[202:203], off offset:512
	global_load_dwordx4 v[244:247], v[202:203], off offset:528
	global_load_dwordx4 v[248:251], v[204:205], off offset:528
	ds_read2_b32 v[206:207], v219 offset1:16
	v_lshl_add_u64 v[132:133], v[176:177], 0, v[184:185]
	v_lshl_add_u64 v[184:185], v[176:177], 0, v[186:187]
	s_waitcnt lgkmcnt(0)
	v_pk_mul_f32 v[32:33], v[32:33], v[206:207] op_sel_hi:[1,0]
	v_pk_mul_f32 v[30:31], v[30:31], v[206:207] op_sel_hi:[1,0]
	v_pk_mul_f32 v[28:29], v[28:29], v[206:207] op_sel_hi:[1,0]
	v_pk_mul_f32 v[26:27], v[26:27], v[206:207] op_sel_hi:[1,0]
	v_mov_b32_e32 v186, v207
	v_pk_mul_f32 v[48:49], v[48:49], v[186:187] op_sel_hi:[1,0]
	v_pk_mul_f32 v[46:47], v[46:47], v[186:187] op_sel_hi:[1,0]
	v_pk_mul_f32 v[44:45], v[44:45], v[186:187] op_sel_hi:[1,0]
	v_pk_mul_f32 v[42:43], v[42:43], v[186:187] op_sel_hi:[1,0]
	s_waitcnt vmcnt(6)
	v_pk_fma_f32 v[32:33], v[140:141], v[32:33], v[136:137]
	v_pk_fma_f32 v[30:31], v[138:139], v[30:31], v[134:135]
	s_waitcnt vmcnt(4)
	v_pk_fma_f32 v[186:187], v[144:145], v[28:29], v[200:201]
	v_pk_fma_f32 v[28:29], v[142:143], v[26:27], v[198:199]
	v_pk_fma_f32 v[48:49], v[140:141], v[48:49], v[136:137]
	v_pk_fma_f32 v[46:47], v[138:139], v[46:47], v[134:135]
	v_pk_fma_f32 v[44:45], v[144:145], v[44:45], v[200:201]
	v_pk_fma_f32 v[42:43], v[142:143], v[42:43], v[198:199]
	v_cvt_pk_bf16_f32 v26, v30, v31
	v_cvt_pk_bf16_f32 v27, v32, v33
	v_cvt_pk_bf16_f32 v28, v28, v29
	v_cvt_pk_bf16_f32 v29, v186, v187
	v_cvt_pk_bf16_f32 v30, v46, v47
	v_cvt_pk_bf16_f32 v31, v48, v49
	v_cvt_pk_bf16_f32 v32, v42, v43
	v_cvt_pk_bf16_f32 v33, v44, v45
	global_store_dwordx4 v[132:133], v[26:29], off
	global_store_dwordx4 v[184:185], v[30:33], off
	ds_read2_b32 v[26:27], v219 offset0:32 offset1:48
	v_lshl_add_u64 v[186:187], v[176:177], 0, v[188:189]
	v_lshl_add_u64 v[188:189], v[176:177], 0, v[190:191]
	s_waitcnt lgkmcnt(0)
	v_pk_mul_f32 v[28:29], v[64:65], v[26:27] op_sel_hi:[1,0]
	v_pk_mul_f32 v[30:31], v[62:63], v[26:27] op_sel_hi:[1,0]
	v_pk_mul_f32 v[32:33], v[60:61], v[26:27] op_sel_hi:[1,0]
	v_pk_mul_f32 v[42:43], v[58:59], v[26:27] op_sel_hi:[1,0]
	v_mov_b32_e32 v26, v27
	v_pk_fma_f32 v[28:29], v[140:141], v[28:29], v[136:137]
	v_pk_fma_f32 v[30:31], v[138:139], v[30:31], v[134:135]
	v_pk_fma_f32 v[32:33], v[144:145], v[32:33], v[200:201]
	v_pk_fma_f32 v[42:43], v[142:143], v[42:43], v[198:199]
	v_pk_mul_f32 v[44:45], v[96:97], v[26:27] op_sel_hi:[1,0]
	v_pk_mul_f32 v[46:47], v[94:95], v[26:27] op_sel_hi:[1,0]
	v_pk_mul_f32 v[48:49], v[92:93], v[26:27] op_sel_hi:[1,0]
	v_pk_mul_f32 v[58:59], v[90:91], v[26:27] op_sel_hi:[1,0]
	v_cvt_pk_bf16_f32 v26, v30, v31
	v_cvt_pk_bf16_f32 v27, v28, v29
	v_cvt_pk_bf16_f32 v28, v42, v43
	v_cvt_pk_bf16_f32 v29, v32, v33
	v_pk_fma_f32 v[30:31], v[140:141], v[44:45], v[136:137]
	v_pk_fma_f32 v[32:33], v[138:139], v[46:47], v[134:135]
	v_pk_fma_f32 v[42:43], v[144:145], v[48:49], v[200:201]
	v_pk_fma_f32 v[44:45], v[142:143], v[58:59], v[198:199]
	global_store_dwordx4 v[186:187], v[26:29], off
	v_lshl_add_u64 v[58:59], v[176:177], 0, v[192:193]
	v_lshl_add_u64 v[60:61], v[176:177], 0, v[194:195]
	v_cvt_pk_bf16_f32 v26, v32, v33
	v_cvt_pk_bf16_f32 v27, v30, v31
	v_cvt_pk_bf16_f32 v28, v44, v45
	v_cvt_pk_bf16_f32 v29, v42, v43
	global_store_dwordx4 v[188:189], v[26:29], off
	ds_read2_b32 v[30:31], v219 offset0:128 offset1:144
	v_lshl_add_u64 v[62:63], v[176:177], 0, v[196:197]
	v_lshl_add_u64 v[64:65], v[176:177], 0, v[130:131]
	s_waitcnt lgkmcnt(0)
	v_pk_mul_f32 v[26:27], v[116:117], v[30:31] op_sel_hi:[1,0]
	v_pk_mul_f32 v[28:29], v[114:115], v[30:31] op_sel_hi:[1,0]
	v_pk_mul_f32 v[32:33], v[112:113], v[30:31] op_sel_hi:[1,0]
	v_pk_mul_f32 v[42:43], v[110:111], v[30:31] op_sel_hi:[1,0]
	v_pk_fma_f32 v[44:45], v[140:141], v[26:27], v[136:137]
	v_pk_fma_f32 v[26:27], v[138:139], v[28:29], v[134:135]
	v_pk_fma_f32 v[32:33], v[144:145], v[32:33], v[200:201]
	v_pk_fma_f32 v[28:29], v[142:143], v[42:43], v[198:199]
	v_cvt_pk_bf16_f32 v26, v26, v27
	v_cvt_pk_bf16_f32 v27, v44, v45
	v_cvt_pk_bf16_f32 v28, v28, v29
	v_cvt_pk_bf16_f32 v29, v32, v33
	global_store_dwordx4 v[58:59], v[26:29], off
	s_nop 1
	v_mov_b32_e32 v26, v31
	v_pk_mul_f32 v[28:29], v[128:129], v[26:27] op_sel_hi:[1,0]
	v_pk_mul_f32 v[30:31], v[126:127], v[26:27] op_sel_hi:[1,0]
	v_pk_mul_f32 v[32:33], v[124:125], v[26:27] op_sel_hi:[1,0]
	v_pk_mul_f32 v[26:27], v[122:123], v[26:27] op_sel_hi:[1,0]
	v_pk_fma_f32 v[28:29], v[140:141], v[28:29], v[136:137]
	v_pk_fma_f32 v[30:31], v[138:139], v[30:31], v[134:135]
	v_pk_fma_f32 v[32:33], v[144:145], v[32:33], v[200:201]
	v_pk_fma_f32 v[42:43], v[142:143], v[26:27], v[198:199]
	v_cvt_pk_bf16_f32 v26, v30, v31
	v_cvt_pk_bf16_f32 v27, v28, v29
	v_cvt_pk_bf16_f32 v28, v42, v43
	v_cvt_pk_bf16_f32 v29, v32, v33
	global_store_dwordx4 v[60:61], v[26:29], off
	ds_read2_b32 v[30:31], v219 offset0:160 offset1:176
	s_waitcnt lgkmcnt(0)
	v_pk_mul_f32 v[42:43], v[106:107], v[30:31] op_sel_hi:[1,0]
	v_pk_mul_f32 v[26:27], v[120:121], v[30:31] op_sel_hi:[1,0]
	v_pk_mul_f32 v[28:29], v[118:119], v[30:31] op_sel_hi:[1,0]
	v_pk_fma_f32 v[32:33], v[140:141], v[26:27], v[136:137]
	v_pk_fma_f32 v[26:27], v[138:139], v[28:29], v[134:135]
	v_pk_mul_f32 v[28:29], v[108:109], v[30:31] op_sel_hi:[1,0]
	v_cvt_pk_bf16_f32 v26, v26, v27
	v_pk_fma_f32 v[44:45], v[144:145], v[28:29], v[200:201]
	v_pk_fma_f32 v[28:29], v[142:143], v[42:43], v[198:199]
	v_cvt_pk_bf16_f32 v27, v32, v33
	v_cvt_pk_bf16_f32 v28, v28, v29
	v_cvt_pk_bf16_f32 v29, v44, v45
	global_store_dwordx4 v[62:63], v[26:29], off
	s_nop 1
	v_mov_b32_e32 v26, v31
	v_pk_mul_f32 v[28:29], v[80:81], v[26:27] op_sel_hi:[1,0]
	v_pk_mul_f32 v[30:31], v[78:79], v[26:27] op_sel_hi:[1,0]
	v_pk_mul_f32 v[32:33], v[76:77], v[26:27] op_sel_hi:[1,0]
	v_pk_mul_f32 v[26:27], v[74:75], v[26:27] op_sel_hi:[1,0]
	v_pk_fma_f32 v[28:29], v[140:141], v[28:29], v[136:137]
	v_pk_fma_f32 v[30:31], v[138:139], v[30:31], v[134:135]
	v_pk_fma_f32 v[32:33], v[144:145], v[32:33], v[200:201]
	v_pk_fma_f32 v[42:43], v[142:143], v[26:27], v[198:199]
	v_cvt_pk_bf16_f32 v26, v30, v31
	v_cvt_pk_bf16_f32 v27, v28, v29
	v_cvt_pk_bf16_f32 v28, v42, v43
	v_cvt_pk_bf16_f32 v29, v32, v33
	global_store_dwordx4 v[64:65], v[26:29], off
	ds_read2_b32 v[74:75], v219 offset1:16
	s_waitcnt lgkmcnt(0)
	v_pk_mul_f32 v[4:5], v[4:5], v[74:75] op_sel_hi:[1,0]
	v_pk_mul_f32 v[2:3], v[2:3], v[74:75] op_sel_hi:[1,0]
	v_pk_mul_f32 v[8:9], v[8:9], v[74:75] op_sel_hi:[1,0]
	v_pk_mul_f32 v[6:7], v[6:7], v[74:75] op_sel_hi:[1,0]
	v_mov_b32_e32 v74, v75
	v_pk_mul_f32 v[12:13], v[12:13], v[74:75] op_sel_hi:[1,0]
	v_pk_mul_f32 v[10:11], v[10:11], v[74:75] op_sel_hi:[1,0]
	v_pk_mul_f32 v[16:17], v[16:17], v[74:75] op_sel_hi:[1,0]
	v_pk_mul_f32 v[14:15], v[14:15], v[74:75] op_sel_hi:[1,0]
	s_waitcnt vmcnt(8)
	v_pk_fma_f32 v[4:5], v[242:243], v[4:5], v[238:239]
	v_pk_fma_f32 v[2:3], v[240:241], v[2:3], v[236:237]
	s_waitcnt vmcnt(8)
	v_pk_fma_f32 v[8:9], v[246:247], v[8:9], v[250:251]
	v_pk_fma_f32 v[6:7], v[244:245], v[6:7], v[248:249]
	v_pk_fma_f32 v[12:13], v[242:243], v[12:13], v[238:239]
	v_pk_fma_f32 v[10:11], v[240:241], v[10:11], v[236:237]
	v_pk_fma_f32 v[16:17], v[246:247], v[16:17], v[250:251]
	v_pk_fma_f32 v[14:15], v[244:245], v[14:15], v[248:249]
	v_cvt_pk_bf16_f32 v2, v2, v3
	v_cvt_pk_bf16_f32 v3, v4, v5
	v_cvt_pk_bf16_f32 v4, v6, v7
	v_cvt_pk_bf16_f32 v5, v8, v9
	v_cvt_pk_bf16_f32 v6, v10, v11
	v_cvt_pk_bf16_f32 v7, v12, v13
	v_cvt_pk_bf16_f32 v8, v14, v15
	v_cvt_pk_bf16_f32 v9, v16, v17
	global_store_dwordx4 v[132:133], v[2:5], off offset:256
	global_store_dwordx4 v[184:185], v[6:9], off offset:256
	ds_read2_b32 v[2:3], v219 offset0:32 offset1:48
	s_waitcnt lgkmcnt(0)
	v_pk_mul_f32 v[4:5], v[20:21], v[2:3] op_sel_hi:[1,0]
	v_pk_mul_f32 v[6:7], v[18:19], v[2:3] op_sel_hi:[1,0]
	v_pk_mul_f32 v[8:9], v[24:25], v[2:3] op_sel_hi:[1,0]
	v_pk_mul_f32 v[10:11], v[22:23], v[2:3] op_sel_hi:[1,0]
	v_mov_b32_e32 v12, v3
	v_pk_fma_f32 v[4:5], v[242:243], v[4:5], v[238:239]
	v_pk_fma_f32 v[2:3], v[240:241], v[6:7], v[236:237]
	v_pk_fma_f32 v[6:7], v[246:247], v[8:9], v[250:251]
	v_pk_fma_f32 v[8:9], v[244:245], v[10:11], v[248:249]
	v_cvt_pk_bf16_f32 v2, v2, v3
	v_cvt_pk_bf16_f32 v3, v4, v5
	v_cvt_pk_bf16_f32 v4, v8, v9
	v_cvt_pk_bf16_f32 v5, v6, v7
	v_pk_mul_f32 v[10:11], v[36:37], v[12:13] op_sel_hi:[1,0]
	v_pk_mul_f32 v[14:15], v[34:35], v[12:13] op_sel_hi:[1,0]
	v_pk_mul_f32 v[16:17], v[40:41], v[12:13] op_sel_hi:[1,0]
	global_store_dwordx4 v[186:187], v[2:5], off offset:256
	v_pk_fma_f32 v[6:7], v[242:243], v[10:11], v[238:239]
	v_pk_fma_f32 v[8:9], v[240:241], v[14:15], v[236:237]
	v_pk_mul_f32 v[2:3], v[38:39], v[12:13] op_sel_hi:[1,0]
	v_pk_fma_f32 v[10:11], v[246:247], v[16:17], v[250:251]
	v_pk_fma_f32 v[4:5], v[244:245], v[2:3], v[248:249]
	v_cvt_pk_bf16_f32 v2, v8, v9
	v_cvt_pk_bf16_f32 v3, v6, v7
	v_cvt_pk_bf16_f32 v4, v4, v5
	v_cvt_pk_bf16_f32 v5, v10, v11
	global_store_dwordx4 v[188:189], v[2:5], off offset:256
	ds_read2_b32 v[6:7], v219 offset0:128 offset1:144
	s_waitcnt lgkmcnt(0)
	v_pk_mul_f32 v[10:11], v[54:55], v[6:7] op_sel_hi:[1,0]
	v_pk_mul_f32 v[2:3], v[52:53], v[6:7] op_sel_hi:[1,0]
	v_pk_mul_f32 v[4:5], v[50:51], v[6:7] op_sel_hi:[1,0]
	v_pk_fma_f32 v[8:9], v[242:243], v[2:3], v[238:239]
	v_pk_fma_f32 v[2:3], v[240:241], v[4:5], v[236:237]
	v_pk_mul_f32 v[4:5], v[56:57], v[6:7] op_sel_hi:[1,0]
	v_cvt_pk_bf16_f32 v2, v2, v3
	v_pk_fma_f32 v[12:13], v[246:247], v[4:5], v[250:251]
	v_pk_fma_f32 v[4:5], v[244:245], v[10:11], v[248:249]
	v_cvt_pk_bf16_f32 v3, v8, v9
	v_cvt_pk_bf16_f32 v4, v4, v5
	v_cvt_pk_bf16_f32 v5, v12, v13
	global_store_dwordx4 v[58:59], v[2:5], off offset:256
	s_nop 1
	v_mov_b32_e32 v2, v7
	v_pk_mul_f32 v[4:5], v[84:85], v[2:3] op_sel_hi:[1,0]
	v_pk_mul_f32 v[6:7], v[82:83], v[2:3] op_sel_hi:[1,0]
	v_pk_mul_f32 v[8:9], v[88:89], v[2:3] op_sel_hi:[1,0]
	v_pk_mul_f32 v[2:3], v[86:87], v[2:3] op_sel_hi:[1,0]
	v_pk_fma_f32 v[4:5], v[242:243], v[4:5], v[238:239]
	v_pk_fma_f32 v[6:7], v[240:241], v[6:7], v[236:237]
	v_pk_fma_f32 v[8:9], v[246:247], v[8:9], v[250:251]
	v_pk_fma_f32 v[10:11], v[244:245], v[2:3], v[248:249]
	v_cvt_pk_bf16_f32 v2, v6, v7
	v_cvt_pk_bf16_f32 v3, v4, v5
	v_cvt_pk_bf16_f32 v4, v10, v11
	v_cvt_pk_bf16_f32 v5, v8, v9
	global_store_dwordx4 v[60:61], v[2:5], off offset:256
	ds_read2_b32 v[6:7], v219 offset0:160 offset1:176
	s_waitcnt lgkmcnt(0)
	v_pk_mul_f32 v[10:11], v[98:99], v[6:7] op_sel_hi:[1,0]
	v_pk_mul_f32 v[2:3], v[104:105], v[6:7] op_sel_hi:[1,0]
	v_pk_mul_f32 v[4:5], v[102:103], v[6:7] op_sel_hi:[1,0]
	v_pk_fma_f32 v[8:9], v[242:243], v[2:3], v[238:239]
	v_pk_fma_f32 v[2:3], v[240:241], v[4:5], v[236:237]
	v_pk_mul_f32 v[4:5], v[100:101], v[6:7] op_sel_hi:[1,0]
	v_cvt_pk_bf16_f32 v2, v2, v3
	v_pk_fma_f32 v[12:13], v[246:247], v[4:5], v[250:251]
	v_pk_fma_f32 v[4:5], v[244:245], v[10:11], v[248:249]
	v_cvt_pk_bf16_f32 v3, v8, v9
	v_cvt_pk_bf16_f32 v4, v4, v5
	v_cvt_pk_bf16_f32 v5, v12, v13
	global_store_dwordx4 v[62:63], v[2:5], off offset:256
	s_nop 1
	v_mov_b32_e32 v2, v7
	v_pk_mul_f32 v[4:5], v[72:73], v[2:3] op_sel_hi:[1,0]
	v_pk_mul_f32 v[6:7], v[70:71], v[2:3] op_sel_hi:[1,0]
	v_pk_mul_f32 v[8:9], v[68:69], v[2:3] op_sel_hi:[1,0]
	v_pk_mul_f32 v[2:3], v[66:67], v[2:3] op_sel_hi:[1,0]
	v_pk_fma_f32 v[4:5], v[242:243], v[4:5], v[238:239]
	v_pk_fma_f32 v[6:7], v[240:241], v[6:7], v[236:237]
	v_pk_fma_f32 v[8:9], v[246:247], v[8:9], v[250:251]
	v_pk_fma_f32 v[10:11], v[244:245], v[2:3], v[248:249]
	v_cvt_pk_bf16_f32 v2, v6, v7
	v_cvt_pk_bf16_f32 v3, v4, v5
	v_cvt_pk_bf16_f32 v4, v10, v11
	v_cvt_pk_bf16_f32 v5, v8, v9
	global_store_dwordx4 v[64:65], v[2:5], off offset:256
	s_cbranch_vccnz .LBB0_873
	s_andn2_b64 vcc, exec, s[12:13]
	s_cbranch_vccnz .LBB0_872
	s_barrier
	s_branch .LBB0_872

.LBB0_1714:
	s_waitcnt vmcnt(0) lgkmcnt(0)
	s_barrier
	global_load_dwordx4 v[6:9], v[146:147], off
	s_waitcnt lgkmcnt(0)
	global_load_dwordx4 v[2:5], v[146:147], off offset:16
	global_load_dwordx4 v[244:247], v[146:147], off offset:512
	global_load_dwordx4 v[248:251], v[146:147], off offset:528
	ds_read2_b32 v[168:169], v190 offset1:16
	v_lshl_add_u64 v[156:157], v[148:149], 0, v[156:157]
	v_lshl_add_u64 v[158:159], v[148:149], 0, v[158:159]
	s_andn2_b64 vcc, exec, s[26:27]
	s_mov_b64 s[26:27], -1
	s_waitcnt lgkmcnt(0)
	v_pk_mul_f32 v[128:129], v[128:129], v[168:169] op_sel_hi:[1,0]
	v_pk_mul_f32 v[126:127], v[126:127], v[168:169] op_sel_hi:[1,0]
	v_pk_mul_f32 v[124:125], v[124:125], v[168:169] op_sel_hi:[1,0]
	v_pk_mul_f32 v[122:123], v[122:123], v[168:169] op_sel_hi:[1,0]
	v_mov_b32_e32 v168, v169
	v_pk_mul_f32 v[170:171], v[112:113], v[168:169] op_sel_hi:[1,0]
	v_pk_mul_f32 v[172:173], v[110:111], v[168:169] op_sel_hi:[1,0]
	v_pk_mul_f32 v[174:175], v[108:109], v[168:169] op_sel_hi:[1,0]
	v_pk_mul_f32 v[168:169], v[106:107], v[168:169] op_sel_hi:[1,0]
	s_waitcnt vmcnt(3)
	v_pk_fma_f32 v[108:109], v[8:9], v[128:129], 0 op_sel_hi:[1,1,0]
	v_pk_fma_f32 v[106:107], v[6:7], v[126:127], 0 op_sel_hi:[1,1,0]
	s_waitcnt vmcnt(2)
	v_pk_fma_f32 v[112:113], v[4:5], v[124:125], 0 op_sel_hi:[1,1,0]
	v_pk_fma_f32 v[110:111], v[2:3], v[122:123], 0 op_sel_hi:[1,1,0]
	v_pk_fma_f32 v[124:125], v[8:9], v[170:171], 0 op_sel_hi:[1,1,0]
	v_pk_fma_f32 v[122:123], v[6:7], v[172:173], 0 op_sel_hi:[1,1,0]
	v_pk_fma_f32 v[128:129], v[4:5], v[174:175], 0 op_sel_hi:[1,1,0]
	v_pk_fma_f32 v[126:127], v[2:3], v[168:169], 0 op_sel_hi:[1,1,0]
	global_store_dwordx4 v[156:157], v[106:109], off
	global_store_dwordx4 v[156:157], v[110:113], off offset:16
	global_store_dwordx4 v[158:159], v[122:125], off
	global_store_dwordx4 v[158:159], v[126:129], off offset:16
	ds_read2_b32 v[110:111], v190 offset0:32 offset1:48
	v_lshl_add_u64 v[106:107], v[148:149], 0, v[160:161]
	v_lshl_add_u64 v[108:109], v[148:149], 0, v[162:163]
	s_waitcnt lgkmcnt(0)
	v_pk_mul_f32 v[96:97], v[96:97], v[110:111] op_sel_hi:[1,0]
	v_pk_mul_f32 v[94:95], v[94:95], v[110:111] op_sel_hi:[1,0]
	v_pk_mul_f32 v[112:113], v[92:93], v[110:111] op_sel_hi:[1,0]
	v_pk_mul_f32 v[122:123], v[90:91], v[110:111] op_sel_hi:[1,0]
	v_mov_b32_e32 v110, v111
	v_pk_mul_f32 v[80:81], v[80:81], v[110:111] op_sel_hi:[1,0]
	v_pk_mul_f32 v[78:79], v[78:79], v[110:111] op_sel_hi:[1,0]
	v_pk_fma_f32 v[92:93], v[8:9], v[96:97], 0 op_sel_hi:[1,1,0]
	v_pk_fma_f32 v[90:91], v[6:7], v[94:95], 0 op_sel_hi:[1,1,0]
	v_pk_fma_f32 v[96:97], v[4:5], v[112:113], 0 op_sel_hi:[1,1,0]
	v_pk_mul_f32 v[112:113], v[76:77], v[110:111] op_sel_hi:[1,0]
	v_pk_mul_f32 v[110:111], v[74:75], v[110:111] op_sel_hi:[1,0]
	v_pk_fma_f32 v[76:77], v[8:9], v[80:81], 0 op_sel_hi:[1,1,0]
	v_pk_fma_f32 v[74:75], v[6:7], v[78:79], 0 op_sel_hi:[1,1,0]
	v_pk_fma_f32 v[94:95], v[2:3], v[122:123], 0 op_sel_hi:[1,1,0]
	global_store_dwordx4 v[106:107], v[90:93], off
	global_store_dwordx4 v[106:107], v[94:97], off offset:16
	v_pk_fma_f32 v[80:81], v[4:5], v[112:113], 0 op_sel_hi:[1,1,0]
	v_pk_fma_f32 v[78:79], v[2:3], v[110:111], 0 op_sel_hi:[1,1,0]
	global_store_dwordx4 v[108:109], v[74:77], off
	global_store_dwordx4 v[108:109], v[78:81], off offset:16
	ds_read2_b32 v[78:79], v190 offset0:128 offset1:144
	v_lshl_add_u64 v[74:75], v[148:149], 0, v[164:165]
	v_lshl_add_u64 v[76:77], v[148:149], 0, v[166:167]
	s_waitcnt lgkmcnt(0)
	v_pk_mul_f32 v[64:65], v[64:65], v[78:79] op_sel_hi:[1,0]
	v_pk_mul_f32 v[62:63], v[62:63], v[78:79] op_sel_hi:[1,0]
	v_pk_mul_f32 v[80:81], v[60:61], v[78:79] op_sel_hi:[1,0]
	v_pk_mul_f32 v[90:91], v[58:59], v[78:79] op_sel_hi:[1,0]
	v_mov_b32_e32 v78, v79
	v_pk_mul_f32 v[48:49], v[48:49], v[78:79] op_sel_hi:[1,0]
	v_pk_mul_f32 v[46:47], v[46:47], v[78:79] op_sel_hi:[1,0]
	v_pk_fma_f32 v[60:61], v[8:9], v[64:65], 0 op_sel_hi:[1,1,0]
	v_pk_fma_f32 v[58:59], v[6:7], v[62:63], 0 op_sel_hi:[1,1,0]
	v_pk_fma_f32 v[64:65], v[4:5], v[80:81], 0 op_sel_hi:[1,1,0]
	v_pk_mul_f32 v[80:81], v[44:45], v[78:79] op_sel_hi:[1,0]
	v_pk_mul_f32 v[78:79], v[42:43], v[78:79] op_sel_hi:[1,0]
	v_pk_fma_f32 v[44:45], v[8:9], v[48:49], 0 op_sel_hi:[1,1,0]
	v_pk_fma_f32 v[42:43], v[6:7], v[46:47], 0 op_sel_hi:[1,1,0]
	v_pk_fma_f32 v[62:63], v[2:3], v[90:91], 0 op_sel_hi:[1,1,0]
	global_store_dwordx4 v[74:75], v[58:61], off
	global_store_dwordx4 v[74:75], v[62:65], off offset:16
	v_pk_fma_f32 v[48:49], v[4:5], v[80:81], 0 op_sel_hi:[1,1,0]
	v_pk_fma_f32 v[46:47], v[2:3], v[78:79], 0 op_sel_hi:[1,1,0]
	global_store_dwordx4 v[76:77], v[42:45], off
	global_store_dwordx4 v[76:77], v[46:49], off offset:16
	ds_read2_b32 v[46:47], v190 offset0:160 offset1:176
	v_lshl_add_u64 v[42:43], v[148:149], 0, v[184:185]
	v_lshl_add_u64 v[44:45], v[148:149], 0, v[186:187]
	s_waitcnt lgkmcnt(0)
	v_pk_mul_f32 v[32:33], v[32:33], v[46:47] op_sel_hi:[1,0]
	v_pk_mul_f32 v[30:31], v[30:31], v[46:47] op_sel_hi:[1,0]
	v_pk_mul_f32 v[48:49], v[28:29], v[46:47] op_sel_hi:[1,0]
	v_pk_mul_f32 v[58:59], v[26:27], v[46:47] op_sel_hi:[1,0]
	v_mov_b32_e32 v46, v47
	v_pk_fma_f32 v[28:29], v[8:9], v[32:33], 0 op_sel_hi:[1,1,0]
	v_pk_fma_f32 v[26:27], v[6:7], v[30:31], 0 op_sel_hi:[1,1,0]
	v_pk_fma_f32 v[32:33], v[4:5], v[48:49], 0 op_sel_hi:[1,1,0]
	v_pk_fma_f32 v[30:31], v[2:3], v[58:59], 0 op_sel_hi:[1,1,0]
	v_pk_mul_f32 v[48:49], v[178:179], v[46:47] op_sel_hi:[1,0]
	v_pk_mul_f32 v[58:59], v[182:183], v[46:47] op_sel_hi:[1,0]
	v_pk_mul_f32 v[60:61], v[176:177], v[46:47] op_sel_hi:[1,0]
	v_pk_mul_f32 v[46:47], v[180:181], v[46:47] op_sel_hi:[1,0]
	v_pk_fma_f32 v[8:9], v[8:9], v[48:49], 0 op_sel_hi:[1,1,0]
	v_pk_fma_f32 v[6:7], v[6:7], v[58:59], 0 op_sel_hi:[1,1,0]
	global_store_dwordx4 v[42:43], v[26:29], off
	global_store_dwordx4 v[42:43], v[30:33], off offset:16
	v_pk_fma_f32 v[4:5], v[4:5], v[60:61], 0 op_sel_hi:[1,1,0]
	v_pk_fma_f32 v[2:3], v[2:3], v[46:47], 0 op_sel_hi:[1,1,0]
	global_store_dwordx4 v[44:45], v[6:9], off
	global_store_dwordx4 v[44:45], v[2:5], off offset:16
	ds_read2_b32 v[26:27], v190 offset1:16
	s_waitcnt lgkmcnt(0)
	v_pk_mul_f32 v[28:29], v[120:121], v[26:27] op_sel_hi:[1,0]
	v_pk_mul_f32 v[30:31], v[118:119], v[26:27] op_sel_hi:[1,0]
	v_pk_mul_f32 v[32:33], v[116:117], v[26:27] op_sel_hi:[1,0]
	v_pk_mul_f32 v[46:47], v[114:115], v[26:27] op_sel_hi:[1,0]
	v_mov_b32_e32 v26, v27
	v_pk_mul_f32 v[48:49], v[104:105], v[26:27] op_sel_hi:[1,0]
	v_pk_mul_f32 v[58:59], v[102:103], v[26:27] op_sel_hi:[1,0]
	v_pk_mul_f32 v[60:61], v[100:101], v[26:27] op_sel_hi:[1,0]
	v_pk_mul_f32 v[62:63], v[98:99], v[26:27] op_sel_hi:[1,0]
	s_waitcnt vmcnt(16)
	v_pk_fma_f32 v[28:29], v[246:247], v[28:29], 0 op_sel_hi:[1,1,0]
	v_pk_fma_f32 v[26:27], v[244:245], v[30:31], 0 op_sel_hi:[1,1,0]
	s_waitcnt vmcnt(16)
	v_pk_fma_f32 v[32:33], v[250:251], v[32:33], 0 op_sel_hi:[1,1,0]
	v_pk_fma_f32 v[30:31], v[248:249], v[46:47], 0 op_sel_hi:[1,1,0]
	v_pk_fma_f32 v[48:49], v[246:247], v[48:49], 0 op_sel_hi:[1,1,0]
	v_pk_fma_f32 v[46:47], v[244:245], v[58:59], 0 op_sel_hi:[1,1,0]
	v_pk_fma_f32 v[60:61], v[250:251], v[60:61], 0 op_sel_hi:[1,1,0]
	v_pk_fma_f32 v[58:59], v[248:249], v[62:63], 0 op_sel_hi:[1,1,0]
	global_store_dwordx4 v[156:157], v[26:29], off offset:512
	global_store_dwordx4 v[156:157], v[30:33], off offset:528
	global_store_dwordx4 v[158:159], v[46:49], off offset:512
	global_store_dwordx4 v[158:159], v[58:61], off offset:528
	ds_read2_b32 v[26:27], v190 offset0:32 offset1:48
	s_waitcnt lgkmcnt(0)
	v_pk_mul_f32 v[28:29], v[88:89], v[26:27] op_sel_hi:[1,0]
	v_pk_mul_f32 v[30:31], v[86:87], v[26:27] op_sel_hi:[1,0]
	v_pk_mul_f32 v[46:47], v[82:83], v[26:27] op_sel_hi:[1,0]
	v_mov_b32_e32 v48, v27
	v_pk_mul_f32 v[32:33], v[84:85], v[26:27] op_sel_hi:[1,0]
	v_pk_fma_f32 v[28:29], v[246:247], v[28:29], 0 op_sel_hi:[1,1,0]
	v_pk_fma_f32 v[26:27], v[244:245], v[30:31], 0 op_sel_hi:[1,1,0]
	v_pk_fma_f32 v[30:31], v[248:249], v[46:47], 0 op_sel_hi:[1,1,0]
	v_pk_mul_f32 v[46:47], v[72:73], v[48:49] op_sel_hi:[1,0]
	v_pk_mul_f32 v[58:59], v[70:71], v[48:49] op_sel_hi:[1,0]
	v_pk_fma_f32 v[32:33], v[250:251], v[32:33], 0 op_sel_hi:[1,1,0]
	v_pk_mul_f32 v[60:61], v[68:69], v[48:49] op_sel_hi:[1,0]
	v_pk_mul_f32 v[48:49], v[66:67], v[48:49] op_sel_hi:[1,0]
	global_store_dwordx4 v[106:107], v[26:29], off offset:512
	global_store_dwordx4 v[106:107], v[30:33], off offset:528
	s_nop 0
	v_pk_fma_f32 v[28:29], v[246:247], v[46:47], 0 op_sel_hi:[1,1,0]
	v_pk_fma_f32 v[26:27], v[244:245], v[58:59], 0 op_sel_hi:[1,1,0]
	v_pk_fma_f32 v[32:33], v[250:251], v[60:61], 0 op_sel_hi:[1,1,0]
	v_pk_fma_f32 v[30:31], v[248:249], v[48:49], 0 op_sel_hi:[1,1,0]
	global_store_dwordx4 v[108:109], v[26:29], off offset:512
	global_store_dwordx4 v[108:109], v[30:33], off offset:528
	ds_read2_b32 v[26:27], v190 offset0:128 offset1:144
	s_waitcnt lgkmcnt(0)
	v_pk_mul_f32 v[28:29], v[56:57], v[26:27] op_sel_hi:[1,0]
	v_pk_mul_f32 v[30:31], v[54:55], v[26:27] op_sel_hi:[1,0]
	v_mov_b32_e32 v48, v27
	v_pk_mul_f32 v[32:33], v[52:53], v[26:27] op_sel_hi:[1,0]
	v_pk_mul_f32 v[46:47], v[50:51], v[26:27] op_sel_hi:[1,0]
	v_pk_fma_f32 v[28:29], v[246:247], v[28:29], 0 op_sel_hi:[1,1,0]
	v_pk_fma_f32 v[26:27], v[244:245], v[30:31], 0 op_sel_hi:[1,1,0]
	v_pk_mul_f32 v[40:41], v[40:41], v[48:49] op_sel_hi:[1,0]
	v_pk_mul_f32 v[38:39], v[38:39], v[48:49] op_sel_hi:[1,0]
	v_pk_fma_f32 v[32:33], v[250:251], v[32:33], 0 op_sel_hi:[1,1,0]
	v_pk_fma_f32 v[30:31], v[248:249], v[46:47], 0 op_sel_hi:[1,1,0]
	v_pk_mul_f32 v[36:37], v[36:37], v[48:49] op_sel_hi:[1,0]
	v_pk_mul_f32 v[34:35], v[34:35], v[48:49] op_sel_hi:[1,0]
	global_store_dwordx4 v[74:75], v[26:29], off offset:512
	global_store_dwordx4 v[74:75], v[30:33], off offset:528
	s_nop 0
	v_pk_fma_f32 v[28:29], v[246:247], v[40:41], 0 op_sel_hi:[1,1,0]
	v_pk_fma_f32 v[26:27], v[244:245], v[38:39], 0 op_sel_hi:[1,1,0]
	v_pk_fma_f32 v[32:33], v[250:251], v[36:37], 0 op_sel_hi:[1,1,0]
	v_pk_fma_f32 v[30:31], v[248:249], v[34:35], 0 op_sel_hi:[1,1,0]
	global_store_dwordx4 v[76:77], v[26:29], off offset:512
	global_store_dwordx4 v[76:77], v[30:33], off offset:528
	ds_read2_b32 v[26:27], v190 offset0:160 offset1:176
	s_waitcnt lgkmcnt(0)
	v_pk_mul_f32 v[24:25], v[24:25], v[26:27] op_sel_hi:[1,0]
	v_pk_mul_f32 v[22:23], v[22:23], v[26:27] op_sel_hi:[1,0]
	v_pk_mul_f32 v[28:29], v[20:21], v[26:27] op_sel_hi:[1,0]
	v_pk_mul_f32 v[30:31], v[18:19], v[26:27] op_sel_hi:[1,0]
	v_mov_b32_e32 v26, v27
	v_pk_mul_f32 v[10:11], v[10:11], v[26:27] op_sel_hi:[1,0]
	v_pk_mul_f32 v[12:13], v[12:13], v[26:27] op_sel_hi:[1,0]
	v_pk_fma_f32 v[20:21], v[246:247], v[24:25], 0 op_sel_hi:[1,1,0]
	v_pk_fma_f32 v[18:19], v[244:245], v[22:23], 0 op_sel_hi:[1,1,0]
	v_pk_mul_f32 v[14:15], v[14:15], v[26:27] op_sel_hi:[1,0]
	v_pk_mul_f32 v[16:17], v[16:17], v[26:27] op_sel_hi:[1,0]
	v_pk_fma_f32 v[246:247], v[246:247], v[10:11], 0 op_sel_hi:[1,1,0]
	v_pk_fma_f32 v[244:245], v[244:245], v[12:13], 0 op_sel_hi:[1,1,0]
	v_pk_fma_f32 v[24:25], v[250:251], v[28:29], 0 op_sel_hi:[1,1,0]
	v_pk_fma_f32 v[22:23], v[248:249], v[30:31], 0 op_sel_hi:[1,1,0]
	global_store_dwordx4 v[42:43], v[18:21], off offset:512
	global_store_dwordx4 v[42:43], v[22:25], off offset:528
	v_pk_fma_f32 v[250:251], v[250:251], v[14:15], 0 op_sel_hi:[1,1,0]
	v_pk_fma_f32 v[248:249], v[248:249], v[16:17], 0 op_sel_hi:[1,1,0]
	global_store_dwordx4 v[44:45], v[244:247], off offset:512
	global_store_dwordx4 v[44:45], v[248:251], off offset:528
	s_cbranch_vccnz .LBB0_1671
	s_andn2_b64 vcc, exec, s[8:9]
	s_cbranch_vccnz .LBB0_1670
	s_barrier
	s_branch .LBB0_1670
